# P2a in-loop prune keeps at most 288 entries per query (was 320): more headroom before the next prune round, fewer rounds
# speedup vs baseline: 1.0465x; 1.0123x over previous
.Lto_nost:
	v_mov_b32_e32 v0, s21
	s_waitcnt lgkmcnt(0)
	s_barrier
	ds_read_b32 v0, v0
	s_waitcnt lgkmcnt(0)
	v_cmp_ne_u32_e32 vcc, s9, v0
	s_and_b64 vcc, exec, vcc
	s_cbranch_vccnz .LBB0_1045
	s_nop 0
	v_readlane_b32 s0, v238, 0
	v_readlane_b32 s1, v238, 32
	s_sub_u32 s0, s0, s33
	s_sub_u32 s0, s0, 0x0
	s_lshr_b32 s78, s0, 2
	s_sub_u32 s1, s1, s33
	s_sub_u32 s1, s1, 0x1000
	s_lshr_b32 s16, s1, 2
	v_readlane_b32 s0, v239, 0
	v_readlane_b32 s1, v239, 32
	s_sub_u32 s0, s0, s33
	s_sub_u32 s0, s0, 0x800
	s_lshr_b32 s61, s0, 2
	s_sub_u32 s1, s1, s33
	s_sub_u32 s1, s1, 0x1800
	s_lshr_b32 s15, s1, 2
	v_readlane_b32 s0, v240, 0
	v_readlane_b32 s1, v240, 32
	s_sub_u32 s0, s0, s33
	s_sub_u32 s0, s0, 0x2000
	s_lshr_b32 s8, s0, 2
	s_sub_u32 s1, s1, s33
	s_sub_u32 s1, s1, 0x3000
	s_lshr_b32 s13, s1, 2
	v_readlane_b32 s0, v241, 0
	v_readlane_b32 s1, v241, 32
	s_sub_u32 s0, s0, s33
	s_sub_u32 s0, s0, 0x2800
	s_lshr_b32 s14, s0, 2
	s_sub_u32 s1, s1, s33
	s_sub_u32 s1, s1, 0x3800
	s_lshr_b32 s5, s1, 2
	v_and_b32_e32 v58, 15, v66
	v_lshlrev_b32_e32 v41, 4, v58
	v_sub_u32_e32 v40, v195, v41
	v_lshrrev_b32_e32 v57, 4, v66
	v_lshl_add_u32 v59, v57, 11, s33
	v_add_u32_e32 v60, v59, v41
	s_mov_b32 s22, 0
	s_mov_b32 s23, 0
	s_cmpk_gt_i32 s78, 0x120
	s_cselect_b32 s0, 0xffff, 0
	s_or_b32 s22, s22, s0
	s_cmpk_gt_i32 s61, 0x120
	s_cselect_b32 s0, 0xffff0000, 0
	s_or_b32 s22, s22, s0
	s_cmpk_gt_i32 s16, 0x120
	s_cselect_b32 s0, 0xffff, 0
	s_or_b32 s23, s23, s0
	s_cmpk_gt_i32 s15, 0x120
	s_cselect_b32 s0, 0xffff0000, 0
	s_or_b32 s23, s23, s0
	s_cmp_eq_u64 s[22:23], 0
	s_cbranch_scc1 .Lp2apr0_end
	v_mov_b32_e32 v32, s78
	v_mov_b32_e32 v41, s61
	v_mov_b32_e32 v42, s16
	v_mov_b32_e32 v43, s15
	s_nop 0
	v_mov_b32_dpp v32, v41 quad_perm:[0,1,2,3] row_mask:0x2 bank_mask:0xf
	v_mov_b32_dpp v32, v42 quad_perm:[0,1,2,3] row_mask:0x4 bank_mask:0xf
	v_mov_b32_dpp v32, v43 quad_perm:[0,1,2,3] row_mask:0x8 bank_mask:0xf
	v_mov_b32_e32 v33, s73
	v_mov_b32_e32 v41, s72
	v_mov_b32_e32 v42, s71
	v_mov_b32_e32 v43, s70
	s_nop 0
	v_mov_b32_dpp v33, v41 quad_perm:[0,1,2,3] row_mask:0x2 bank_mask:0xf
	v_mov_b32_dpp v33, v42 quad_perm:[0,1,2,3] row_mask:0x4 bank_mask:0xf
	v_mov_b32_dpp v33, v43 quad_perm:[0,1,2,3] row_mask:0x8 bank_mask:0xf
	ds_read_b128 v[0:3], v60
	ds_read_b128 v[4:7], v60 offset:256
	ds_read_b128 v[8:11], v60 offset:512
	ds_read_b128 v[12:15], v60 offset:768
	ds_read_b128 v[16:19], v60 offset:1024
	ds_read_b128 v[20:23], v60 offset:1280
	ds_read_b128 v[24:27], v60 offset:1536
	ds_read_b128 v[28:31], v60 offset:1792
	v_lshlrev_b32_e32 v41, 2, v58
	v_sub_u32_e32 v41, v32, v41
	s_waitcnt lgkmcnt(0)
	v_mov_b32_e32 v47, 16
	v_subrev_u32_e32 v42, 256, v41
	v_med3_i32 v43, v42, 0, 4
	v_add_u32_e32 v47, v47, v43
	v_cmp_lt_i32_e32 vcc, 0, v42
	v_cmp_lt_i32_e64 s[0:1], 1, v42
	v_cmp_lt_i32_e64 s[2:3], 2, v42
	v_cndmask_b32_e32 v16, 0, v16, vcc
	v_cmp_lt_i32_e32 vcc, 3, v42
	v_cndmask_b32_e64 v17, 0, v17, s[0:1]
	v_cndmask_b32_e64 v18, 0, v18, s[2:3]
	v_cndmask_b32_e32 v19, 0, v19, vcc
	v_subrev_u32_e32 v42, 320, v41
	v_med3_i32 v43, v42, 0, 4
	v_add_u32_e32 v47, v47, v43
	v_cmp_lt_i32_e32 vcc, 0, v42
	v_cmp_lt_i32_e64 s[0:1], 1, v42
	v_cmp_lt_i32_e64 s[2:3], 2, v42
	v_cndmask_b32_e32 v20, 0, v20, vcc
	v_cmp_lt_i32_e32 vcc, 3, v42
	v_cndmask_b32_e64 v21, 0, v21, s[0:1]
	v_cndmask_b32_e64 v22, 0, v22, s[2:3]
	v_cndmask_b32_e32 v23, 0, v23, vcc
	v_subrev_u32_e32 v42, 384, v41
	v_med3_i32 v43, v42, 0, 4
	v_add_u32_e32 v47, v47, v43
	v_cmp_lt_i32_e32 vcc, 0, v42
	v_cmp_lt_i32_e64 s[0:1], 1, v42
	v_cmp_lt_i32_e64 s[2:3], 2, v42
	v_cndmask_b32_e32 v24, 0, v24, vcc
	v_cmp_lt_i32_e32 vcc, 3, v42
	v_cndmask_b32_e64 v25, 0, v25, s[0:1]
	v_cndmask_b32_e64 v26, 0, v26, s[2:3]
	v_cndmask_b32_e32 v27, 0, v27, vcc
	v_subrev_u32_e32 v42, 448, v41
	v_med3_i32 v43, v42, 0, 4
	v_add_u32_e32 v47, v47, v43
	v_cmp_lt_i32_e32 vcc, 0, v42
	v_cmp_lt_i32_e64 s[0:1], 1, v42
	v_cmp_lt_i32_e64 s[2:3], 2, v42
	v_cndmask_b32_e32 v28, 0, v28, vcc
	v_cmp_lt_i32_e32 vcc, 3, v42
	v_cndmask_b32_e64 v29, 0, v29, s[0:1]
	v_cndmask_b32_e64 v30, 0, v30, s[2:3]
	v_cndmask_b32_e32 v31, 0, v31, vcc
	v_max3_u32 v35, v0, v1, v2
	v_max3_u32 v35, v3, v4, v35
	v_max3_u32 v35, v5, v6, v35
	v_max3_u32 v35, v7, v8, v35
	v_max3_u32 v35, v9, v10, v35
	v_max3_u32 v35, v11, v12, v35
	v_max3_u32 v35, v13, v14, v35
	v_max3_u32 v35, v15, v16, v35
	v_max3_u32 v35, v17, v18, v35
	v_max3_u32 v35, v19, v20, v35
	v_max3_u32 v35, v21, v22, v35
	v_max3_u32 v35, v23, v24, v35
	v_max3_u32 v35, v25, v26, v35
	v_max3_u32 v35, v27, v28, v35
	v_max3_u32 v35, v29, v30, v35
	v_max_u32_e32 v35, v31, v35
	s_nop 1
	v_max_u32_dpp v35, v35, v35 row_ror:1 row_mask:0xf bank_mask:0xf
	s_nop 1
	v_max_u32_dpp v35, v35, v35 row_ror:2 row_mask:0xf bank_mask:0xf
	s_nop 1
	v_max_u32_dpp v35, v35, v35 row_ror:4 row_mask:0xf bank_mask:0xf
	s_nop 1
	v_max_u32_dpp v35, v35, v35 row_ror:8 row_mask:0xf bank_mask:0xf
	v_and_b32_e32 v34, 0xffffe000, v33
	v_cmp_eq_u32_e32 vcc, 0, v33
	s_and_b64 vcc, vcc, s[22:23]
	s_cbranch_vccz .Lp2apr0_nomin
	v_add_u32_e32 v41, -1, v0
	v_add_u32_e32 v42, -1, v1
	v_min_u32_e32 v43, v41, v42
	v_add_u32_e32 v41, -1, v2
	v_add_u32_e32 v42, -1, v3
	v_min3_u32 v43, v41, v42, v43
	v_add_u32_e32 v41, -1, v4
	v_add_u32_e32 v42, -1, v5
	v_min3_u32 v43, v41, v42, v43
	v_add_u32_e32 v41, -1, v6
	v_add_u32_e32 v42, -1, v7
	v_min3_u32 v43, v41, v42, v43
	v_add_u32_e32 v41, -1, v8
	v_add_u32_e32 v42, -1, v9
	v_min3_u32 v43, v41, v42, v43
	v_add_u32_e32 v41, -1, v10
	v_add_u32_e32 v42, -1, v11
	v_min3_u32 v43, v41, v42, v43
	v_add_u32_e32 v41, -1, v12
	v_add_u32_e32 v42, -1, v13
	v_min3_u32 v43, v41, v42, v43
	v_add_u32_e32 v41, -1, v14
	v_add_u32_e32 v42, -1, v15
	v_min3_u32 v43, v41, v42, v43
	v_add_u32_e32 v41, -1, v16
	v_add_u32_e32 v42, -1, v17
	v_min3_u32 v43, v41, v42, v43
	v_add_u32_e32 v41, -1, v18
	v_add_u32_e32 v42, -1, v19
	v_min3_u32 v43, v41, v42, v43
	v_add_u32_e32 v41, -1, v20
	v_add_u32_e32 v42, -1, v21
	v_min3_u32 v43, v41, v42, v43
	v_add_u32_e32 v41, -1, v22
	v_add_u32_e32 v42, -1, v23
	v_min3_u32 v43, v41, v42, v43
	v_add_u32_e32 v41, -1, v24
	v_add_u32_e32 v42, -1, v25
	v_min3_u32 v43, v41, v42, v43
	v_add_u32_e32 v41, -1, v26
	v_add_u32_e32 v42, -1, v27
	v_min3_u32 v43, v41, v42, v43
	v_add_u32_e32 v41, -1, v28
	v_add_u32_e32 v42, -1, v29
	v_min3_u32 v43, v41, v42, v43
	v_add_u32_e32 v41, -1, v30
	v_add_u32_e32 v42, -1, v31
	v_min3_u32 v43, v41, v42, v43
	s_nop 1
	v_min_u32_dpp v43, v43, v43 row_ror:1 row_mask:0xf bank_mask:0xf
	s_nop 1
	v_min_u32_dpp v43, v43, v43 row_ror:2 row_mask:0xf bank_mask:0xf
	s_nop 1
	v_min_u32_dpp v43, v43, v43 row_ror:4 row_mask:0xf bank_mask:0xf
	s_nop 1
	v_min_u32_dpp v43, v43, v43 row_ror:8 row_mask:0xf bank_mask:0xf
	v_add_u32_e32 v43, 1, v43
	v_cmp_eq_u32_e32 vcc, 0, v33
	s_nop 1
	v_cndmask_b32_e32 v34, v34, v43, vcc

.Lp2apr0_iter:
	v_sub_u32_e32 v38, v35, v34
	v_or_b32_e32 v41, 1, v38
	v_ffbh_u32_e32 v41, v41
	v_sub_u32_e32 v41, 26, v41
	v_max_i32_e32 v39, 0, v41
	v_mov_b32_e32 v36, 0
	v_or_b32_e32 v42, 32, v36
	v_lshlrev_b32_e32 v41, v39, v42
	v_add_u32_e64 v43, v34, v41 clamp
	v_mov_b32_e32 v44, 0
	v_cmp_ge_u32_e32 vcc, v0, v43
	v_cmp_ge_u32_e64 s[0:1], v1, v43
	v_cmp_ge_u32_e64 s[2:3], v2, v43
	v_addc_co_u32_e64 v44, vcc, 0, v44, vcc
	v_cmp_ge_u32_e32 vcc, v3, v43
	v_addc_co_u32_e64 v44, s[0:1], 0, v44, s[0:1]
	v_cmp_ge_u32_e64 s[0:1], v4, v43
	v_addc_co_u32_e64 v44, s[2:3], 0, v44, s[2:3]
	v_cmp_ge_u32_e64 s[2:3], v5, v43
	v_addc_co_u32_e64 v44, vcc, 0, v44, vcc
	v_cmp_ge_u32_e32 vcc, v6, v43
	v_addc_co_u32_e64 v44, s[0:1], 0, v44, s[0:1]
	v_cmp_ge_u32_e64 s[0:1], v7, v43
	v_addc_co_u32_e64 v44, s[2:3], 0, v44, s[2:3]
	v_cmp_ge_u32_e64 s[2:3], v8, v43
	v_addc_co_u32_e64 v44, vcc, 0, v44, vcc
	v_cmp_ge_u32_e32 vcc, v9, v43
	v_addc_co_u32_e64 v44, s[0:1], 0, v44, s[0:1]
	v_cmp_ge_u32_e64 s[0:1], v10, v43
	v_addc_co_u32_e64 v44, s[2:3], 0, v44, s[2:3]
	v_cmp_ge_u32_e64 s[2:3], v11, v43
	v_addc_co_u32_e64 v44, vcc, 0, v44, vcc
	v_cmp_ge_u32_e32 vcc, v12, v43
	v_addc_co_u32_e64 v44, s[0:1], 0, v44, s[0:1]
	v_cmp_ge_u32_e64 s[0:1], v13, v43
	v_addc_co_u32_e64 v44, s[2:3], 0, v44, s[2:3]
	v_cmp_ge_u32_e64 s[2:3], v14, v43
	v_addc_co_u32_e64 v44, vcc, 0, v44, vcc
	v_cmp_ge_u32_e32 vcc, v15, v43
	v_addc_co_u32_e64 v44, s[0:1], 0, v44, s[0:1]
	v_cmp_ge_u32_e64 s[0:1], v16, v43
	v_addc_co_u32_e64 v44, s[2:3], 0, v44, s[2:3]
	v_cmp_ge_u32_e64 s[2:3], v17, v43
	v_addc_co_u32_e64 v44, vcc, 0, v44, vcc
	v_cmp_ge_u32_e32 vcc, v18, v43
	v_addc_co_u32_e64 v44, s[0:1], 0, v44, s[0:1]
	v_cmp_ge_u32_e64 s[0:1], v19, v43
	v_addc_co_u32_e64 v44, s[2:3], 0, v44, s[2:3]
	v_cmp_ge_u32_e64 s[2:3], v20, v43
	v_addc_co_u32_e64 v44, vcc, 0, v44, vcc
	v_cmp_ge_u32_e32 vcc, v21, v43
	v_addc_co_u32_e64 v44, s[0:1], 0, v44, s[0:1]
	v_cmp_ge_u32_e64 s[0:1], v22, v43
	v_addc_co_u32_e64 v44, s[2:3], 0, v44, s[2:3]
	v_cmp_ge_u32_e64 s[2:3], v23, v43
	v_addc_co_u32_e64 v44, vcc, 0, v44, vcc
	v_cmp_ge_u32_e32 vcc, v24, v43
	v_addc_co_u32_e64 v44, s[0:1], 0, v44, s[0:1]
	v_cmp_ge_u32_e64 s[0:1], v25, v43
	v_addc_co_u32_e64 v44, s[2:3], 0, v44, s[2:3]
	v_cmp_ge_u32_e64 s[2:3], v26, v43
	v_addc_co_u32_e64 v44, vcc, 0, v44, vcc
	v_cmp_ge_u32_e32 vcc, v27, v43
	v_addc_co_u32_e64 v44, s[0:1], 0, v44, s[0:1]
	v_cmp_ge_u32_e64 s[0:1], v28, v43
	v_addc_co_u32_e64 v44, s[2:3], 0, v44, s[2:3]
	v_cmp_ge_u32_e64 s[2:3], v29, v43
	v_addc_co_u32_e64 v44, vcc, 0, v44, vcc
	v_cmp_ge_u32_e32 vcc, v30, v43
	v_addc_co_u32_e64 v44, s[0:1], 0, v44, s[0:1]
	v_cmp_ge_u32_e64 s[0:1], v31, v43
	v_addc_co_u32_e64 v44, s[2:3], 0, v44, s[2:3]
	v_addc_co_u32_e64 v44, vcc, 0, v44, vcc
	v_addc_co_u32_e64 v44, s[0:1], 0, v44, s[0:1]
	v_mov_b32_e32 v45, v44
	s_nop 1
	v_add_u32_dpp v45, v45, v45 row_ror:1 row_mask:0xf bank_mask:0xf
	s_nop 1
	v_add_u32_dpp v45, v45, v45 row_ror:2 row_mask:0xf bank_mask:0xf
	s_nop 1
	v_add_u32_dpp v45, v45, v45 row_ror:4 row_mask:0xf bank_mask:0xf
	s_nop 1
	v_add_u32_dpp v45, v45, v45 row_ror:8 row_mask:0xf bank_mask:0xf
	s_nop 0
	v_cmp_le_u32_e32 vcc, 0x100, v45
	s_nop 1
	v_cndmask_b32_e32 v36, v36, v42, vcc
	v_cndmask_b32_e32 v46, v46, v45, vcc
	v_cndmask_b32_e32 v47, v47, v44, vcc
	v_or_b32_e32 v42, 16, v36
	v_lshlrev_b32_e32 v41, v39, v42
	v_add_u32_e64 v43, v34, v41 clamp
	v_mov_b32_e32 v44, 0
	v_cmp_ge_u32_e32 vcc, v0, v43
	v_cmp_ge_u32_e64 s[0:1], v1, v43
	v_cmp_ge_u32_e64 s[2:3], v2, v43
	v_addc_co_u32_e64 v44, vcc, 0, v44, vcc
	v_cmp_ge_u32_e32 vcc, v3, v43
	v_addc_co_u32_e64 v44, s[0:1], 0, v44, s[0:1]
	v_cmp_ge_u32_e64 s[0:1], v4, v43
	v_addc_co_u32_e64 v44, s[2:3], 0, v44, s[2:3]
	v_cmp_ge_u32_e64 s[2:3], v5, v43
	v_addc_co_u32_e64 v44, vcc, 0, v44, vcc
	v_cmp_ge_u32_e32 vcc, v6, v43
	v_addc_co_u32_e64 v44, s[0:1], 0, v44, s[0:1]
	v_cmp_ge_u32_e64 s[0:1], v7, v43
	v_addc_co_u32_e64 v44, s[2:3], 0, v44, s[2:3]
	v_cmp_ge_u32_e64 s[2:3], v8, v43
	v_addc_co_u32_e64 v44, vcc, 0, v44, vcc
	v_cmp_ge_u32_e32 vcc, v9, v43
	v_addc_co_u32_e64 v44, s[0:1], 0, v44, s[0:1]
	v_cmp_ge_u32_e64 s[0:1], v10, v43
	v_addc_co_u32_e64 v44, s[2:3], 0, v44, s[2:3]
	v_cmp_ge_u32_e64 s[2:3], v11, v43
	v_addc_co_u32_e64 v44, vcc, 0, v44, vcc
	v_cmp_ge_u32_e32 vcc, v12, v43
	v_addc_co_u32_e64 v44, s[0:1], 0, v44, s[0:1]
	v_cmp_ge_u32_e64 s[0:1], v13, v43
	v_addc_co_u32_e64 v44, s[2:3], 0, v44, s[2:3]
	v_cmp_ge_u32_e64 s[2:3], v14, v43
	v_addc_co_u32_e64 v44, vcc, 0, v44, vcc
	v_cmp_ge_u32_e32 vcc, v15, v43
	v_addc_co_u32_e64 v44, s[0:1], 0, v44, s[0:1]
	v_cmp_ge_u32_e64 s[0:1], v16, v43
	v_addc_co_u32_e64 v44, s[2:3], 0, v44, s[2:3]
	v_cmp_ge_u32_e64 s[2:3], v17, v43
	v_addc_co_u32_e64 v44, vcc, 0, v44, vcc
	v_cmp_ge_u32_e32 vcc, v18, v43
	v_addc_co_u32_e64 v44, s[0:1], 0, v44, s[0:1]
	v_cmp_ge_u32_e64 s[0:1], v19, v43
	v_addc_co_u32_e64 v44, s[2:3], 0, v44, s[2:3]
	v_cmp_ge_u32_e64 s[2:3], v20, v43
	v_addc_co_u32_e64 v44, vcc, 0, v44, vcc
	v_cmp_ge_u32_e32 vcc, v21, v43
	v_addc_co_u32_e64 v44, s[0:1], 0, v44, s[0:1]
	v_cmp_ge_u32_e64 s[0:1], v22, v43
	v_addc_co_u32_e64 v44, s[2:3], 0, v44, s[2:3]
	v_cmp_ge_u32_e64 s[2:3], v23, v43
	v_addc_co_u32_e64 v44, vcc, 0, v44, vcc
	v_cmp_ge_u32_e32 vcc, v24, v43
	v_addc_co_u32_e64 v44, s[0:1], 0, v44, s[0:1]
	v_cmp_ge_u32_e64 s[0:1], v25, v43
	v_addc_co_u32_e64 v44, s[2:3], 0, v44, s[2:3]
	v_cmp_ge_u32_e64 s[2:3], v26, v43
	v_addc_co_u32_e64 v44, vcc, 0, v44, vcc
	v_cmp_ge_u32_e32 vcc, v27, v43
	v_addc_co_u32_e64 v44, s[0:1], 0, v44, s[0:1]
	v_cmp_ge_u32_e64 s[0:1], v28, v43
	v_addc_co_u32_e64 v44, s[2:3], 0, v44, s[2:3]
	v_cmp_ge_u32_e64 s[2:3], v29, v43
	v_addc_co_u32_e64 v44, vcc, 0, v44, vcc
	v_cmp_ge_u32_e32 vcc, v30, v43
	v_addc_co_u32_e64 v44, s[0:1], 0, v44, s[0:1]
	v_cmp_ge_u32_e64 s[0:1], v31, v43
	v_addc_co_u32_e64 v44, s[2:3], 0, v44, s[2:3]
	v_addc_co_u32_e64 v44, vcc, 0, v44, vcc
	v_addc_co_u32_e64 v44, s[0:1], 0, v44, s[0:1]
	v_mov_b32_e32 v45, v44
	s_nop 1
	v_add_u32_dpp v45, v45, v45 row_ror:1 row_mask:0xf bank_mask:0xf
	s_nop 1
	v_add_u32_dpp v45, v45, v45 row_ror:2 row_mask:0xf bank_mask:0xf
	s_nop 1
	v_add_u32_dpp v45, v45, v45 row_ror:4 row_mask:0xf bank_mask:0xf
	s_nop 1
	v_add_u32_dpp v45, v45, v45 row_ror:8 row_mask:0xf bank_mask:0xf
	s_nop 0
	v_cmp_le_u32_e32 vcc, 0x100, v45
	s_nop 1
	v_cndmask_b32_e32 v36, v36, v42, vcc
	v_cndmask_b32_e32 v46, v46, v45, vcc
	v_cndmask_b32_e32 v47, v47, v44, vcc
	v_or_b32_e32 v42, 8, v36
	v_lshlrev_b32_e32 v41, v39, v42
	v_add_u32_e64 v43, v34, v41 clamp
	v_mov_b32_e32 v44, 0
	v_cmp_ge_u32_e32 vcc, v0, v43
	v_cmp_ge_u32_e64 s[0:1], v1, v43
	v_cmp_ge_u32_e64 s[2:3], v2, v43
	v_addc_co_u32_e64 v44, vcc, 0, v44, vcc
	v_cmp_ge_u32_e32 vcc, v3, v43
	v_addc_co_u32_e64 v44, s[0:1], 0, v44, s[0:1]
	v_cmp_ge_u32_e64 s[0:1], v4, v43
	v_addc_co_u32_e64 v44, s[2:3], 0, v44, s[2:3]
	v_cmp_ge_u32_e64 s[2:3], v5, v43
	v_addc_co_u32_e64 v44, vcc, 0, v44, vcc
	v_cmp_ge_u32_e32 vcc, v6, v43
	v_addc_co_u32_e64 v44, s[0:1], 0, v44, s[0:1]
	v_cmp_ge_u32_e64 s[0:1], v7, v43
	v_addc_co_u32_e64 v44, s[2:3], 0, v44, s[2:3]
	v_cmp_ge_u32_e64 s[2:3], v8, v43
	v_addc_co_u32_e64 v44, vcc, 0, v44, vcc
	v_cmp_ge_u32_e32 vcc, v9, v43
	v_addc_co_u32_e64 v44, s[0:1], 0, v44, s[0:1]
	v_cmp_ge_u32_e64 s[0:1], v10, v43
	v_addc_co_u32_e64 v44, s[2:3], 0, v44, s[2:3]
	v_cmp_ge_u32_e64 s[2:3], v11, v43
	v_addc_co_u32_e64 v44, vcc, 0, v44, vcc
	v_cmp_ge_u32_e32 vcc, v12, v43
	v_addc_co_u32_e64 v44, s[0:1], 0, v44, s[0:1]
	v_cmp_ge_u32_e64 s[0:1], v13, v43
	v_addc_co_u32_e64 v44, s[2:3], 0, v44, s[2:3]
	v_cmp_ge_u32_e64 s[2:3], v14, v43
	v_addc_co_u32_e64 v44, vcc, 0, v44, vcc
	v_cmp_ge_u32_e32 vcc, v15, v43
	v_addc_co_u32_e64 v44, s[0:1], 0, v44, s[0:1]
	v_cmp_ge_u32_e64 s[0:1], v16, v43
	v_addc_co_u32_e64 v44, s[2:3], 0, v44, s[2:3]
	v_cmp_ge_u32_e64 s[2:3], v17, v43
	v_addc_co_u32_e64 v44, vcc, 0, v44, vcc
	v_cmp_ge_u32_e32 vcc, v18, v43
	v_addc_co_u32_e64 v44, s[0:1], 0, v44, s[0:1]
	v_cmp_ge_u32_e64 s[0:1], v19, v43
	v_addc_co_u32_e64 v44, s[2:3], 0, v44, s[2:3]
	v_cmp_ge_u32_e64 s[2:3], v20, v43
	v_addc_co_u32_e64 v44, vcc, 0, v44, vcc
	v_cmp_ge_u32_e32 vcc, v21, v43
	v_addc_co_u32_e64 v44, s[0:1], 0, v44, s[0:1]
	v_cmp_ge_u32_e64 s[0:1], v22, v43
	v_addc_co_u32_e64 v44, s[2:3], 0, v44, s[2:3]
	v_cmp_ge_u32_e64 s[2:3], v23, v43
	v_addc_co_u32_e64 v44, vcc, 0, v44, vcc
	v_cmp_ge_u32_e32 vcc, v24, v43
	v_addc_co_u32_e64 v44, s[0:1], 0, v44, s[0:1]
	v_cmp_ge_u32_e64 s[0:1], v25, v43
	v_addc_co_u32_e64 v44, s[2:3], 0, v44, s[2:3]
	v_cmp_ge_u32_e64 s[2:3], v26, v43
	v_addc_co_u32_e64 v44, vcc, 0, v44, vcc
	v_cmp_ge_u32_e32 vcc, v27, v43
	v_addc_co_u32_e64 v44, s[0:1], 0, v44, s[0:1]
	v_cmp_ge_u32_e64 s[0:1], v28, v43
	v_addc_co_u32_e64 v44, s[2:3], 0, v44, s[2:3]
	v_cmp_ge_u32_e64 s[2:3], v29, v43
	v_addc_co_u32_e64 v44, vcc, 0, v44, vcc
	v_cmp_ge_u32_e32 vcc, v30, v43
	v_addc_co_u32_e64 v44, s[0:1], 0, v44, s[0:1]
	v_cmp_ge_u32_e64 s[0:1], v31, v43
	v_addc_co_u32_e64 v44, s[2:3], 0, v44, s[2:3]
	v_addc_co_u32_e64 v44, vcc, 0, v44, vcc
	v_addc_co_u32_e64 v44, s[0:1], 0, v44, s[0:1]
	v_mov_b32_e32 v45, v44
	s_nop 1
	v_add_u32_dpp v45, v45, v45 row_ror:1 row_mask:0xf bank_mask:0xf
	s_nop 1
	v_add_u32_dpp v45, v45, v45 row_ror:2 row_mask:0xf bank_mask:0xf
	s_nop 1
	v_add_u32_dpp v45, v45, v45 row_ror:4 row_mask:0xf bank_mask:0xf
	s_nop 1
	v_add_u32_dpp v45, v45, v45 row_ror:8 row_mask:0xf bank_mask:0xf
	s_nop 0
	v_cmp_le_u32_e32 vcc, 0x100, v45
	s_nop 1
	v_cndmask_b32_e32 v36, v36, v42, vcc
	v_cndmask_b32_e32 v46, v46, v45, vcc
	v_cndmask_b32_e32 v47, v47, v44, vcc
	v_or_b32_e32 v42, 4, v36
	v_lshlrev_b32_e32 v41, v39, v42
	v_add_u32_e64 v43, v34, v41 clamp
	v_mov_b32_e32 v44, 0
	v_cmp_ge_u32_e32 vcc, v0, v43
	v_cmp_ge_u32_e64 s[0:1], v1, v43
	v_cmp_ge_u32_e64 s[2:3], v2, v43
	v_addc_co_u32_e64 v44, vcc, 0, v44, vcc
	v_cmp_ge_u32_e32 vcc, v3, v43
	v_addc_co_u32_e64 v44, s[0:1], 0, v44, s[0:1]
	v_cmp_ge_u32_e64 s[0:1], v4, v43
	v_addc_co_u32_e64 v44, s[2:3], 0, v44, s[2:3]
	v_cmp_ge_u32_e64 s[2:3], v5, v43
	v_addc_co_u32_e64 v44, vcc, 0, v44, vcc
	v_cmp_ge_u32_e32 vcc, v6, v43
	v_addc_co_u32_e64 v44, s[0:1], 0, v44, s[0:1]
	v_cmp_ge_u32_e64 s[0:1], v7, v43
	v_addc_co_u32_e64 v44, s[2:3], 0, v44, s[2:3]
	v_cmp_ge_u32_e64 s[2:3], v8, v43
	v_addc_co_u32_e64 v44, vcc, 0, v44, vcc
	v_cmp_ge_u32_e32 vcc, v9, v43
	v_addc_co_u32_e64 v44, s[0:1], 0, v44, s[0:1]
	v_cmp_ge_u32_e64 s[0:1], v10, v43
	v_addc_co_u32_e64 v44, s[2:3], 0, v44, s[2:3]
	v_cmp_ge_u32_e64 s[2:3], v11, v43
	v_addc_co_u32_e64 v44, vcc, 0, v44, vcc
	v_cmp_ge_u32_e32 vcc, v12, v43
	v_addc_co_u32_e64 v44, s[0:1], 0, v44, s[0:1]
	v_cmp_ge_u32_e64 s[0:1], v13, v43
	v_addc_co_u32_e64 v44, s[2:3], 0, v44, s[2:3]
	v_cmp_ge_u32_e64 s[2:3], v14, v43
	v_addc_co_u32_e64 v44, vcc, 0, v44, vcc
	v_cmp_ge_u32_e32 vcc, v15, v43
	v_addc_co_u32_e64 v44, s[0:1], 0, v44, s[0:1]
	v_cmp_ge_u32_e64 s[0:1], v16, v43
	v_addc_co_u32_e64 v44, s[2:3], 0, v44, s[2:3]
	v_cmp_ge_u32_e64 s[2:3], v17, v43
	v_addc_co_u32_e64 v44, vcc, 0, v44, vcc
	v_cmp_ge_u32_e32 vcc, v18, v43
	v_addc_co_u32_e64 v44, s[0:1], 0, v44, s[0:1]
	v_cmp_ge_u32_e64 s[0:1], v19, v43
	v_addc_co_u32_e64 v44, s[2:3], 0, v44, s[2:3]
	v_cmp_ge_u32_e64 s[2:3], v20, v43
	v_addc_co_u32_e64 v44, vcc, 0, v44, vcc
	v_cmp_ge_u32_e32 vcc, v21, v43
	v_addc_co_u32_e64 v44, s[0:1], 0, v44, s[0:1]
	v_cmp_ge_u32_e64 s[0:1], v22, v43
	v_addc_co_u32_e64 v44, s[2:3], 0, v44, s[2:3]
	v_cmp_ge_u32_e64 s[2:3], v23, v43
	v_addc_co_u32_e64 v44, vcc, 0, v44, vcc
	v_cmp_ge_u32_e32 vcc, v24, v43
	v_addc_co_u32_e64 v44, s[0:1], 0, v44, s[0:1]
	v_cmp_ge_u32_e64 s[0:1], v25, v43
	v_addc_co_u32_e64 v44, s[2:3], 0, v44, s[2:3]
	v_cmp_ge_u32_e64 s[2:3], v26, v43
	v_addc_co_u32_e64 v44, vcc, 0, v44, vcc
	v_cmp_ge_u32_e32 vcc, v27, v43
	v_addc_co_u32_e64 v44, s[0:1], 0, v44, s[0:1]
	v_cmp_ge_u32_e64 s[0:1], v28, v43
	v_addc_co_u32_e64 v44, s[2:3], 0, v44, s[2:3]
	v_cmp_ge_u32_e64 s[2:3], v29, v43
	v_addc_co_u32_e64 v44, vcc, 0, v44, vcc
	v_cmp_ge_u32_e32 vcc, v30, v43
	v_addc_co_u32_e64 v44, s[0:1], 0, v44, s[0:1]
	v_cmp_ge_u32_e64 s[0:1], v31, v43
	v_addc_co_u32_e64 v44, s[2:3], 0, v44, s[2:3]
	v_addc_co_u32_e64 v44, vcc, 0, v44, vcc
	v_addc_co_u32_e64 v44, s[0:1], 0, v44, s[0:1]
	v_mov_b32_e32 v45, v44
	s_nop 1
	v_add_u32_dpp v45, v45, v45 row_ror:1 row_mask:0xf bank_mask:0xf
	s_nop 1
	v_add_u32_dpp v45, v45, v45 row_ror:2 row_mask:0xf bank_mask:0xf
	s_nop 1
	v_add_u32_dpp v45, v45, v45 row_ror:4 row_mask:0xf bank_mask:0xf
	s_nop 1
	v_add_u32_dpp v45, v45, v45 row_ror:8 row_mask:0xf bank_mask:0xf
	s_nop 0
	v_cmp_le_u32_e32 vcc, 0x100, v45
	s_nop 1
	v_cndmask_b32_e32 v36, v36, v42, vcc
	v_cndmask_b32_e32 v46, v46, v45, vcc
	v_cndmask_b32_e32 v47, v47, v44, vcc
	v_or_b32_e32 v42, 2, v36
	v_lshlrev_b32_e32 v41, v39, v42
	v_add_u32_e64 v43, v34, v41 clamp
	v_mov_b32_e32 v44, 0
	v_cmp_ge_u32_e32 vcc, v0, v43
	v_cmp_ge_u32_e64 s[0:1], v1, v43
	v_cmp_ge_u32_e64 s[2:3], v2, v43
	v_addc_co_u32_e64 v44, vcc, 0, v44, vcc
	v_cmp_ge_u32_e32 vcc, v3, v43
	v_addc_co_u32_e64 v44, s[0:1], 0, v44, s[0:1]
	v_cmp_ge_u32_e64 s[0:1], v4, v43
	v_addc_co_u32_e64 v44, s[2:3], 0, v44, s[2:3]
	v_cmp_ge_u32_e64 s[2:3], v5, v43
	v_addc_co_u32_e64 v44, vcc, 0, v44, vcc
	v_cmp_ge_u32_e32 vcc, v6, v43
	v_addc_co_u32_e64 v44, s[0:1], 0, v44, s[0:1]
	v_cmp_ge_u32_e64 s[0:1], v7, v43
	v_addc_co_u32_e64 v44, s[2:3], 0, v44, s[2:3]
	v_cmp_ge_u32_e64 s[2:3], v8, v43
	v_addc_co_u32_e64 v44, vcc, 0, v44, vcc
	v_cmp_ge_u32_e32 vcc, v9, v43
	v_addc_co_u32_e64 v44, s[0:1], 0, v44, s[0:1]
	v_cmp_ge_u32_e64 s[0:1], v10, v43
	v_addc_co_u32_e64 v44, s[2:3], 0, v44, s[2:3]
	v_cmp_ge_u32_e64 s[2:3], v11, v43
	v_addc_co_u32_e64 v44, vcc, 0, v44, vcc
	v_cmp_ge_u32_e32 vcc, v12, v43
	v_addc_co_u32_e64 v44, s[0:1], 0, v44, s[0:1]
	v_cmp_ge_u32_e64 s[0:1], v13, v43
	v_addc_co_u32_e64 v44, s[2:3], 0, v44, s[2:3]
	v_cmp_ge_u32_e64 s[2:3], v14, v43
	v_addc_co_u32_e64 v44, vcc, 0, v44, vcc
	v_cmp_ge_u32_e32 vcc, v15, v43
	v_addc_co_u32_e64 v44, s[0:1], 0, v44, s[0:1]
	v_cmp_ge_u32_e64 s[0:1], v16, v43
	v_addc_co_u32_e64 v44, s[2:3], 0, v44, s[2:3]
	v_cmp_ge_u32_e64 s[2:3], v17, v43
	v_addc_co_u32_e64 v44, vcc, 0, v44, vcc
	v_cmp_ge_u32_e32 vcc, v18, v43
	v_addc_co_u32_e64 v44, s[0:1], 0, v44, s[0:1]
	v_cmp_ge_u32_e64 s[0:1], v19, v43
	v_addc_co_u32_e64 v44, s[2:3], 0, v44, s[2:3]
	v_cmp_ge_u32_e64 s[2:3], v20, v43
	v_addc_co_u32_e64 v44, vcc, 0, v44, vcc
	v_cmp_ge_u32_e32 vcc, v21, v43
	v_addc_co_u32_e64 v44, s[0:1], 0, v44, s[0:1]
	v_cmp_ge_u32_e64 s[0:1], v22, v43
	v_addc_co_u32_e64 v44, s[2:3], 0, v44, s[2:3]
	v_cmp_ge_u32_e64 s[2:3], v23, v43
	v_addc_co_u32_e64 v44, vcc, 0, v44, vcc
	v_cmp_ge_u32_e32 vcc, v24, v43
	v_addc_co_u32_e64 v44, s[0:1], 0, v44, s[0:1]
	v_cmp_ge_u32_e64 s[0:1], v25, v43
	v_addc_co_u32_e64 v44, s[2:3], 0, v44, s[2:3]
	v_cmp_ge_u32_e64 s[2:3], v26, v43
	v_addc_co_u32_e64 v44, vcc, 0, v44, vcc
	v_cmp_ge_u32_e32 vcc, v27, v43
	v_addc_co_u32_e64 v44, s[0:1], 0, v44, s[0:1]
	v_cmp_ge_u32_e64 s[0:1], v28, v43
	v_addc_co_u32_e64 v44, s[2:3], 0, v44, s[2:3]
	v_cmp_ge_u32_e64 s[2:3], v29, v43
	v_addc_co_u32_e64 v44, vcc, 0, v44, vcc
	v_cmp_ge_u32_e32 vcc, v30, v43
	v_addc_co_u32_e64 v44, s[0:1], 0, v44, s[0:1]
	v_cmp_ge_u32_e64 s[0:1], v31, v43
	v_addc_co_u32_e64 v44, s[2:3], 0, v44, s[2:3]
	v_addc_co_u32_e64 v44, vcc, 0, v44, vcc
	v_addc_co_u32_e64 v44, s[0:1], 0, v44, s[0:1]
	v_mov_b32_e32 v45, v44
	s_nop 1
	v_add_u32_dpp v45, v45, v45 row_ror:1 row_mask:0xf bank_mask:0xf
	s_nop 1
	v_add_u32_dpp v45, v45, v45 row_ror:2 row_mask:0xf bank_mask:0xf
	s_nop 1
	v_add_u32_dpp v45, v45, v45 row_ror:4 row_mask:0xf bank_mask:0xf
	s_nop 1
	v_add_u32_dpp v45, v45, v45 row_ror:8 row_mask:0xf bank_mask:0xf
	s_nop 0
	v_cmp_le_u32_e32 vcc, 0x100, v45
	s_nop 1
	v_cndmask_b32_e32 v36, v36, v42, vcc
	v_cndmask_b32_e32 v46, v46, v45, vcc
	v_cndmask_b32_e32 v47, v47, v44, vcc
	v_or_b32_e32 v42, 1, v36
	v_lshlrev_b32_e32 v41, v39, v42
	v_add_u32_e64 v43, v34, v41 clamp
	v_mov_b32_e32 v44, 0
	v_cmp_ge_u32_e32 vcc, v0, v43
	v_cmp_ge_u32_e64 s[0:1], v1, v43
	v_cmp_ge_u32_e64 s[2:3], v2, v43
	v_addc_co_u32_e64 v44, vcc, 0, v44, vcc
	v_cmp_ge_u32_e32 vcc, v3, v43
	v_addc_co_u32_e64 v44, s[0:1], 0, v44, s[0:1]
	v_cmp_ge_u32_e64 s[0:1], v4, v43
	v_addc_co_u32_e64 v44, s[2:3], 0, v44, s[2:3]
	v_cmp_ge_u32_e64 s[2:3], v5, v43
	v_addc_co_u32_e64 v44, vcc, 0, v44, vcc
	v_cmp_ge_u32_e32 vcc, v6, v43
	v_addc_co_u32_e64 v44, s[0:1], 0, v44, s[0:1]
	v_cmp_ge_u32_e64 s[0:1], v7, v43
	v_addc_co_u32_e64 v44, s[2:3], 0, v44, s[2:3]
	v_cmp_ge_u32_e64 s[2:3], v8, v43
	v_addc_co_u32_e64 v44, vcc, 0, v44, vcc
	v_cmp_ge_u32_e32 vcc, v9, v43
	v_addc_co_u32_e64 v44, s[0:1], 0, v44, s[0:1]
	v_cmp_ge_u32_e64 s[0:1], v10, v43
	v_addc_co_u32_e64 v44, s[2:3], 0, v44, s[2:3]
	v_cmp_ge_u32_e64 s[2:3], v11, v43
	v_addc_co_u32_e64 v44, vcc, 0, v44, vcc
	v_cmp_ge_u32_e32 vcc, v12, v43
	v_addc_co_u32_e64 v44, s[0:1], 0, v44, s[0:1]
	v_cmp_ge_u32_e64 s[0:1], v13, v43
	v_addc_co_u32_e64 v44, s[2:3], 0, v44, s[2:3]
	v_cmp_ge_u32_e64 s[2:3], v14, v43
	v_addc_co_u32_e64 v44, vcc, 0, v44, vcc
	v_cmp_ge_u32_e32 vcc, v15, v43
	v_addc_co_u32_e64 v44, s[0:1], 0, v44, s[0:1]
	v_cmp_ge_u32_e64 s[0:1], v16, v43
	v_addc_co_u32_e64 v44, s[2:3], 0, v44, s[2:3]
	v_cmp_ge_u32_e64 s[2:3], v17, v43
	v_addc_co_u32_e64 v44, vcc, 0, v44, vcc
	v_cmp_ge_u32_e32 vcc, v18, v43
	v_addc_co_u32_e64 v44, s[0:1], 0, v44, s[0:1]
	v_cmp_ge_u32_e64 s[0:1], v19, v43
	v_addc_co_u32_e64 v44, s[2:3], 0, v44, s[2:3]
	v_cmp_ge_u32_e64 s[2:3], v20, v43
	v_addc_co_u32_e64 v44, vcc, 0, v44, vcc
	v_cmp_ge_u32_e32 vcc, v21, v43
	v_addc_co_u32_e64 v44, s[0:1], 0, v44, s[0:1]
	v_cmp_ge_u32_e64 s[0:1], v22, v43
	v_addc_co_u32_e64 v44, s[2:3], 0, v44, s[2:3]
	v_cmp_ge_u32_e64 s[2:3], v23, v43
	v_addc_co_u32_e64 v44, vcc, 0, v44, vcc
	v_cmp_ge_u32_e32 vcc, v24, v43
	v_addc_co_u32_e64 v44, s[0:1], 0, v44, s[0:1]
	v_cmp_ge_u32_e64 s[0:1], v25, v43
	v_addc_co_u32_e64 v44, s[2:3], 0, v44, s[2:3]
	v_cmp_ge_u32_e64 s[2:3], v26, v43
	v_addc_co_u32_e64 v44, vcc, 0, v44, vcc
	v_cmp_ge_u32_e32 vcc, v27, v43
	v_addc_co_u32_e64 v44, s[0:1], 0, v44, s[0:1]
	v_cmp_ge_u32_e64 s[0:1], v28, v43
	v_addc_co_u32_e64 v44, s[2:3], 0, v44, s[2:3]
	v_cmp_ge_u32_e64 s[2:3], v29, v43
	v_addc_co_u32_e64 v44, vcc, 0, v44, vcc
	v_cmp_ge_u32_e32 vcc, v30, v43
	v_addc_co_u32_e64 v44, s[0:1], 0, v44, s[0:1]
	v_cmp_ge_u32_e64 s[0:1], v31, v43
	v_addc_co_u32_e64 v44, s[2:3], 0, v44, s[2:3]
	v_addc_co_u32_e64 v44, vcc, 0, v44, vcc
	v_addc_co_u32_e64 v44, s[0:1], 0, v44, s[0:1]
	v_mov_b32_e32 v45, v44
	s_nop 1
	v_add_u32_dpp v45, v45, v45 row_ror:1 row_mask:0xf bank_mask:0xf
	s_nop 1
	v_add_u32_dpp v45, v45, v45 row_ror:2 row_mask:0xf bank_mask:0xf
	s_nop 1
	v_add_u32_dpp v45, v45, v45 row_ror:4 row_mask:0xf bank_mask:0xf
	s_nop 1
	v_add_u32_dpp v45, v45, v45 row_ror:8 row_mask:0xf bank_mask:0xf
	s_nop 0
	v_cmp_le_u32_e32 vcc, 0x100, v45
	s_nop 1
	v_cndmask_b32_e32 v36, v36, v42, vcc
	v_cndmask_b32_e32 v46, v46, v45, vcc
	v_cndmask_b32_e32 v47, v47, v44, vcc
	v_lshlrev_b32_e32 v41, v39, v36
	v_add_u32_e32 v41, v34, v41
	v_cmp_ge_u32_e32 vcc, 0x120, v46
	v_cmp_eq_u32_e64 s[0:1], 0, v39
	v_lshlrev_b32_e32 v42, v39, v200
	v_add_u32_e32 v42, -1, v42
	s_or_b64 vcc, vcc, s[0:1]
	s_andn2_b64 s[0:1], vcc, s[50:51]
	s_nor_b64 s[2:3], vcc, s[50:51]
	s_or_b64 s[50:51], s[50:51], vcc
	v_add_u32_e64 v42, v41, v42 clamp
	v_min_u32_e32 v42, v42, v35
	v_cndmask_b32_e64 v37, v37, v41, s[0:1]
	v_cndmask_b32_e64 v62, v62, v47, s[0:1]
	v_cndmask_b32_e64 v35, v35, v42, s[2:3]
	v_cndmask_b32_e64 v34, v34, v41, s[2:3]
	s_cmp_eq_u64 s[50:51], -1
	s_cbranch_scc0 .Lp2apr0_iter
	s_mov_b64 exec, s[22:23]
	v_mov_b32_e32 v61, v62
	s_nop 1
	v_add_u32_dpp v61, v61, v61 row_shr:1 row_mask:0xf bank_mask:0xf bound_ctrl:1
	s_nop 1
	v_add_u32_dpp v61, v61, v61 row_shr:2 row_mask:0xf bank_mask:0xf bound_ctrl:1
	s_nop 1
	v_add_u32_dpp v61, v61, v61 row_shr:4 row_mask:0xf bank_mask:0xf bound_ctrl:1
	s_nop 1
	v_add_u32_dpp v61, v61, v61 row_shr:8 row_mask:0xf bank_mask:0xf bound_ctrl:1
	v_sub_u32_e32 v62, v61, v62
	v_lshl_add_u32 v41, v62, 2, v59
	v_cmpx_ge_u32_e32 vcc, v0, v37
	ds_write_b32 v41, v0
	v_add_u32_e32 v62, 1, v62
	s_mov_b64 exec, s[22:23]
	v_lshl_add_u32 v41, v62, 2, v59
	v_cmpx_ge_u32_e32 vcc, v1, v37
	ds_write_b32 v41, v1
	v_add_u32_e32 v62, 1, v62
	s_mov_b64 exec, s[22:23]
	v_lshl_add_u32 v41, v62, 2, v59
	v_cmpx_ge_u32_e32 vcc, v2, v37
	ds_write_b32 v41, v2
	v_add_u32_e32 v62, 1, v62
	s_mov_b64 exec, s[22:23]
	v_lshl_add_u32 v41, v62, 2, v59
	v_cmpx_ge_u32_e32 vcc, v3, v37
	ds_write_b32 v41, v3
	v_add_u32_e32 v62, 1, v62
	s_mov_b64 exec, s[22:23]
	v_lshl_add_u32 v41, v62, 2, v59
	v_cmpx_ge_u32_e32 vcc, v4, v37
	ds_write_b32 v41, v4
	v_add_u32_e32 v62, 1, v62
	s_mov_b64 exec, s[22:23]
	v_lshl_add_u32 v41, v62, 2, v59
	v_cmpx_ge_u32_e32 vcc, v5, v37
	ds_write_b32 v41, v5
	v_add_u32_e32 v62, 1, v62
	s_mov_b64 exec, s[22:23]
	v_lshl_add_u32 v41, v62, 2, v59
	v_cmpx_ge_u32_e32 vcc, v6, v37
	ds_write_b32 v41, v6
	v_add_u32_e32 v62, 1, v62
	s_mov_b64 exec, s[22:23]
	v_lshl_add_u32 v41, v62, 2, v59
	v_cmpx_ge_u32_e32 vcc, v7, v37
	ds_write_b32 v41, v7
	v_add_u32_e32 v62, 1, v62
	s_mov_b64 exec, s[22:23]
	v_lshl_add_u32 v41, v62, 2, v59
	v_cmpx_ge_u32_e32 vcc, v8, v37
	ds_write_b32 v41, v8
	v_add_u32_e32 v62, 1, v62
	s_mov_b64 exec, s[22:23]
	v_lshl_add_u32 v41, v62, 2, v59
	v_cmpx_ge_u32_e32 vcc, v9, v37
	ds_write_b32 v41, v9
	v_add_u32_e32 v62, 1, v62
	s_mov_b64 exec, s[22:23]
	v_lshl_add_u32 v41, v62, 2, v59
	v_cmpx_ge_u32_e32 vcc, v10, v37
	ds_write_b32 v41, v10
	v_add_u32_e32 v62, 1, v62
	s_mov_b64 exec, s[22:23]
	v_lshl_add_u32 v41, v62, 2, v59
	v_cmpx_ge_u32_e32 vcc, v11, v37
	ds_write_b32 v41, v11
	v_add_u32_e32 v62, 1, v62
	s_mov_b64 exec, s[22:23]
	v_lshl_add_u32 v41, v62, 2, v59
	v_cmpx_ge_u32_e32 vcc, v12, v37
	ds_write_b32 v41, v12
	v_add_u32_e32 v62, 1, v62
	s_mov_b64 exec, s[22:23]
	v_lshl_add_u32 v41, v62, 2, v59
	v_cmpx_ge_u32_e32 vcc, v13, v37
	ds_write_b32 v41, v13
	v_add_u32_e32 v62, 1, v62
	s_mov_b64 exec, s[22:23]
	v_lshl_add_u32 v41, v62, 2, v59
	v_cmpx_ge_u32_e32 vcc, v14, v37
	ds_write_b32 v41, v14
	v_add_u32_e32 v62, 1, v62
	s_mov_b64 exec, s[22:23]
	v_lshl_add_u32 v41, v62, 2, v59
	v_cmpx_ge_u32_e32 vcc, v15, v37
	ds_write_b32 v41, v15
	v_add_u32_e32 v62, 1, v62
	s_mov_b64 exec, s[22:23]
	v_lshl_add_u32 v41, v62, 2, v59
	v_cmpx_ge_u32_e32 vcc, v16, v37
	ds_write_b32 v41, v16
	v_add_u32_e32 v62, 1, v62
	s_mov_b64 exec, s[22:23]
	v_lshl_add_u32 v41, v62, 2, v59
	v_cmpx_ge_u32_e32 vcc, v17, v37
	ds_write_b32 v41, v17
	v_add_u32_e32 v62, 1, v62
	s_mov_b64 exec, s[22:23]
	v_lshl_add_u32 v41, v62, 2, v59
	v_cmpx_ge_u32_e32 vcc, v18, v37
	ds_write_b32 v41, v18
	v_add_u32_e32 v62, 1, v62
	s_mov_b64 exec, s[22:23]
	v_lshl_add_u32 v41, v62, 2, v59
	v_cmpx_ge_u32_e32 vcc, v19, v37
	ds_write_b32 v41, v19
	v_add_u32_e32 v62, 1, v62
	s_mov_b64 exec, s[22:23]
	v_lshl_add_u32 v41, v62, 2, v59
	v_cmpx_ge_u32_e32 vcc, v20, v37
	ds_write_b32 v41, v20
	v_add_u32_e32 v62, 1, v62
	s_mov_b64 exec, s[22:23]
	v_lshl_add_u32 v41, v62, 2, v59
	v_cmpx_ge_u32_e32 vcc, v21, v37
	ds_write_b32 v41, v21
	v_add_u32_e32 v62, 1, v62
	s_mov_b64 exec, s[22:23]
	v_lshl_add_u32 v41, v62, 2, v59
	v_cmpx_ge_u32_e32 vcc, v22, v37
	ds_write_b32 v41, v22
	v_add_u32_e32 v62, 1, v62
	s_mov_b64 exec, s[22:23]
	v_lshl_add_u32 v41, v62, 2, v59
	v_cmpx_ge_u32_e32 vcc, v23, v37
	ds_write_b32 v41, v23
	v_add_u32_e32 v62, 1, v62
	s_mov_b64 exec, s[22:23]
	v_lshl_add_u32 v41, v62, 2, v59
	v_cmpx_ge_u32_e32 vcc, v24, v37
	ds_write_b32 v41, v24
	v_add_u32_e32 v62, 1, v62
	s_mov_b64 exec, s[22:23]
	v_lshl_add_u32 v41, v62, 2, v59
	v_cmpx_ge_u32_e32 vcc, v25, v37
	ds_write_b32 v41, v25
	v_add_u32_e32 v62, 1, v62
	s_mov_b64 exec, s[22:23]
	v_lshl_add_u32 v41, v62, 2, v59
	v_cmpx_ge_u32_e32 vcc, v26, v37
	ds_write_b32 v41, v26
	v_add_u32_e32 v62, 1, v62
	s_mov_b64 exec, s[22:23]
	v_lshl_add_u32 v41, v62, 2, v59
	v_cmpx_ge_u32_e32 vcc, v27, v37
	ds_write_b32 v41, v27
	v_add_u32_e32 v62, 1, v62
	s_mov_b64 exec, s[22:23]
	v_lshl_add_u32 v41, v62, 2, v59
	v_cmpx_ge_u32_e32 vcc, v28, v37
	ds_write_b32 v41, v28
	v_add_u32_e32 v62, 1, v62
	s_mov_b64 exec, s[22:23]
	v_lshl_add_u32 v41, v62, 2, v59
	v_cmpx_ge_u32_e32 vcc, v29, v37
	ds_write_b32 v41, v29
	v_add_u32_e32 v62, 1, v62
	s_mov_b64 exec, s[22:23]
	v_lshl_add_u32 v41, v62, 2, v59
	v_cmpx_ge_u32_e32 vcc, v30, v37
	ds_write_b32 v41, v30
	v_add_u32_e32 v62, 1, v62
	s_mov_b64 exec, s[22:23]
	v_lshl_add_u32 v41, v62, 2, v59
	v_cmpx_ge_u32_e32 vcc, v31, v37
	ds_write_b32 v41, v31
	v_add_u32_e32 v62, 1, v62
	s_mov_b64 exec, s[22:23]
	s_mov_b64 exec, -1
	v_and_b32_e32 v41, 0xffffe000, v37
	v_ashrrev_i32_e32 v42, 31, v41
	v_not_b32_e32 v42, v42
	v_or_b32_e32 v42, 0x80000000, v42
	v_xor_b32_e32 v63, v41, v42
	s_cmpk_lt_i32 s78, 0x121
	s_cbranch_scc1 .Lp2apr0_o0
	v_readlane_b32 s0, v63, 0
	v_readlane_b32 s73, v37, 0
	v_readlane_b32 s78, v61, 15
	v_mov_b32_e32 v231, s0
.Lp2apr0_o0:
	s_cmpk_lt_i32 s61, 0x121
	s_cbranch_scc1 .Lp2apr0_o1
	v_readlane_b32 s0, v63, 16
	v_readlane_b32 s72, v37, 16
	v_readlane_b32 s61, v61, 31
	v_mov_b32_e32 v229, s0
.Lp2apr0_o1:
	s_cmpk_lt_i32 s16, 0x121
	s_cbranch_scc1 .Lp2apr0_o2
	v_readlane_b32 s0, v63, 32
	v_readlane_b32 s71, v37, 32
	v_readlane_b32 s16, v61, 47
	v_mov_b32_e32 v230, s0
.Lp2apr0_o2:
	s_cmpk_lt_i32 s15, 0x121
	s_cbranch_scc1 .Lp2apr0_o3
	v_readlane_b32 s0, v63, 48
	v_readlane_b32 s70, v37, 48
	v_readlane_b32 s15, v61, 63
	v_mov_b32_e32 v232, s0
.Lp2apr0_o3:
.Lp2apr0_end:
	v_add_u32_e32 v59, 0x2000, v59
	v_add_u32_e32 v60, 0x2000, v60
	s_mov_b32 s22, 0
	s_mov_b32 s23, 0
	s_cmpk_gt_i32 s8, 0x120
	s_cselect_b32 s0, 0xffff, 0
	s_or_b32 s22, s22, s0
	s_cmpk_gt_i32 s14, 0x120
	s_cselect_b32 s0, 0xffff0000, 0
	s_or_b32 s22, s22, s0
	s_cmpk_gt_i32 s13, 0x120
	s_cselect_b32 s0, 0xffff, 0
	s_or_b32 s23, s23, s0
	s_cmpk_gt_i32 s5, 0x120
	s_cselect_b32 s0, 0xffff0000, 0
	s_or_b32 s23, s23, s0
	s_cmp_eq_u64 s[22:23], 0
	s_cbranch_scc1 .Lp2apr1_end
	v_mov_b32_e32 v32, s8
	v_mov_b32_e32 v41, s14
	v_mov_b32_e32 v42, s13
	v_mov_b32_e32 v43, s5
	s_nop 0
	v_mov_b32_dpp v32, v41 quad_perm:[0,1,2,3] row_mask:0x2 bank_mask:0xf
	v_mov_b32_dpp v32, v42 quad_perm:[0,1,2,3] row_mask:0x4 bank_mask:0xf
	v_mov_b32_dpp v32, v43 quad_perm:[0,1,2,3] row_mask:0x8 bank_mask:0xf
	v_mov_b32_e32 v33, s74
	v_mov_b32_e32 v41, s75
	v_mov_b32_e32 v42, s76
	v_mov_b32_e32 v43, s77
	s_nop 0
	v_mov_b32_dpp v33, v41 quad_perm:[0,1,2,3] row_mask:0x2 bank_mask:0xf
	v_mov_b32_dpp v33, v42 quad_perm:[0,1,2,3] row_mask:0x4 bank_mask:0xf
	v_mov_b32_dpp v33, v43 quad_perm:[0,1,2,3] row_mask:0x8 bank_mask:0xf
	ds_read_b128 v[0:3], v60
	ds_read_b128 v[4:7], v60 offset:256
	ds_read_b128 v[8:11], v60 offset:512
	ds_read_b128 v[12:15], v60 offset:768
	ds_read_b128 v[16:19], v60 offset:1024
	ds_read_b128 v[20:23], v60 offset:1280
	ds_read_b128 v[24:27], v60 offset:1536
	ds_read_b128 v[28:31], v60 offset:1792
	v_lshlrev_b32_e32 v41, 2, v58
	v_sub_u32_e32 v41, v32, v41
	s_waitcnt lgkmcnt(0)
	v_mov_b32_e32 v47, 16
	v_subrev_u32_e32 v42, 256, v41
	v_med3_i32 v43, v42, 0, 4
	v_add_u32_e32 v47, v47, v43
	v_cmp_lt_i32_e32 vcc, 0, v42
	v_cmp_lt_i32_e64 s[0:1], 1, v42
	v_cmp_lt_i32_e64 s[2:3], 2, v42
	v_cndmask_b32_e32 v16, 0, v16, vcc
	v_cmp_lt_i32_e32 vcc, 3, v42
	v_cndmask_b32_e64 v17, 0, v17, s[0:1]
	v_cndmask_b32_e64 v18, 0, v18, s[2:3]
	v_cndmask_b32_e32 v19, 0, v19, vcc
	v_subrev_u32_e32 v42, 320, v41
	v_med3_i32 v43, v42, 0, 4
	v_add_u32_e32 v47, v47, v43
	v_cmp_lt_i32_e32 vcc, 0, v42
	v_cmp_lt_i32_e64 s[0:1], 1, v42
	v_cmp_lt_i32_e64 s[2:3], 2, v42
	v_cndmask_b32_e32 v20, 0, v20, vcc
	v_cmp_lt_i32_e32 vcc, 3, v42
	v_cndmask_b32_e64 v21, 0, v21, s[0:1]
	v_cndmask_b32_e64 v22, 0, v22, s[2:3]
	v_cndmask_b32_e32 v23, 0, v23, vcc
	v_subrev_u32_e32 v42, 384, v41
	v_med3_i32 v43, v42, 0, 4
	v_add_u32_e32 v47, v47, v43
	v_cmp_lt_i32_e32 vcc, 0, v42
	v_cmp_lt_i32_e64 s[0:1], 1, v42
	v_cmp_lt_i32_e64 s[2:3], 2, v42
	v_cndmask_b32_e32 v24, 0, v24, vcc
	v_cmp_lt_i32_e32 vcc, 3, v42
	v_cndmask_b32_e64 v25, 0, v25, s[0:1]
	v_cndmask_b32_e64 v26, 0, v26, s[2:3]
	v_cndmask_b32_e32 v27, 0, v27, vcc
	v_subrev_u32_e32 v42, 448, v41
	v_med3_i32 v43, v42, 0, 4
	v_add_u32_e32 v47, v47, v43
	v_cmp_lt_i32_e32 vcc, 0, v42
	v_cmp_lt_i32_e64 s[0:1], 1, v42
	v_cmp_lt_i32_e64 s[2:3], 2, v42
	v_cndmask_b32_e32 v28, 0, v28, vcc
	v_cmp_lt_i32_e32 vcc, 3, v42
	v_cndmask_b32_e64 v29, 0, v29, s[0:1]
	v_cndmask_b32_e64 v30, 0, v30, s[2:3]
	v_cndmask_b32_e32 v31, 0, v31, vcc
	v_max3_u32 v35, v0, v1, v2
	v_max3_u32 v35, v3, v4, v35
	v_max3_u32 v35, v5, v6, v35
	v_max3_u32 v35, v7, v8, v35
	v_max3_u32 v35, v9, v10, v35
	v_max3_u32 v35, v11, v12, v35
	v_max3_u32 v35, v13, v14, v35
	v_max3_u32 v35, v15, v16, v35
	v_max3_u32 v35, v17, v18, v35
	v_max3_u32 v35, v19, v20, v35
	v_max3_u32 v35, v21, v22, v35
	v_max3_u32 v35, v23, v24, v35
	v_max3_u32 v35, v25, v26, v35
	v_max3_u32 v35, v27, v28, v35
	v_max3_u32 v35, v29, v30, v35
	v_max_u32_e32 v35, v31, v35
	s_nop 1
	v_max_u32_dpp v35, v35, v35 row_ror:1 row_mask:0xf bank_mask:0xf
	s_nop 1
	v_max_u32_dpp v35, v35, v35 row_ror:2 row_mask:0xf bank_mask:0xf
	s_nop 1
	v_max_u32_dpp v35, v35, v35 row_ror:4 row_mask:0xf bank_mask:0xf
	s_nop 1
	v_max_u32_dpp v35, v35, v35 row_ror:8 row_mask:0xf bank_mask:0xf
	v_and_b32_e32 v34, 0xffffe000, v33
	v_cmp_eq_u32_e32 vcc, 0, v33
	s_and_b64 vcc, vcc, s[22:23]
	s_cbranch_vccz .Lp2apr1_nomin
	v_add_u32_e32 v41, -1, v0
	v_add_u32_e32 v42, -1, v1
	v_min_u32_e32 v43, v41, v42
	v_add_u32_e32 v41, -1, v2
	v_add_u32_e32 v42, -1, v3
	v_min3_u32 v43, v41, v42, v43
	v_add_u32_e32 v41, -1, v4
	v_add_u32_e32 v42, -1, v5
	v_min3_u32 v43, v41, v42, v43
	v_add_u32_e32 v41, -1, v6
	v_add_u32_e32 v42, -1, v7
	v_min3_u32 v43, v41, v42, v43
	v_add_u32_e32 v41, -1, v8
	v_add_u32_e32 v42, -1, v9
	v_min3_u32 v43, v41, v42, v43
	v_add_u32_e32 v41, -1, v10
	v_add_u32_e32 v42, -1, v11
	v_min3_u32 v43, v41, v42, v43
	v_add_u32_e32 v41, -1, v12
	v_add_u32_e32 v42, -1, v13
	v_min3_u32 v43, v41, v42, v43
	v_add_u32_e32 v41, -1, v14
	v_add_u32_e32 v42, -1, v15
	v_min3_u32 v43, v41, v42, v43
	v_add_u32_e32 v41, -1, v16
	v_add_u32_e32 v42, -1, v17
	v_min3_u32 v43, v41, v42, v43
	v_add_u32_e32 v41, -1, v18
	v_add_u32_e32 v42, -1, v19
	v_min3_u32 v43, v41, v42, v43
	v_add_u32_e32 v41, -1, v20
	v_add_u32_e32 v42, -1, v21
	v_min3_u32 v43, v41, v42, v43
	v_add_u32_e32 v41, -1, v22
	v_add_u32_e32 v42, -1, v23
	v_min3_u32 v43, v41, v42, v43
	v_add_u32_e32 v41, -1, v24
	v_add_u32_e32 v42, -1, v25
	v_min3_u32 v43, v41, v42, v43
	v_add_u32_e32 v41, -1, v26
	v_add_u32_e32 v42, -1, v27
	v_min3_u32 v43, v41, v42, v43
	v_add_u32_e32 v41, -1, v28
	v_add_u32_e32 v42, -1, v29
	v_min3_u32 v43, v41, v42, v43
	v_add_u32_e32 v41, -1, v30
	v_add_u32_e32 v42, -1, v31
	v_min3_u32 v43, v41, v42, v43
	s_nop 1
	v_min_u32_dpp v43, v43, v43 row_ror:1 row_mask:0xf bank_mask:0xf
	s_nop 1
	v_min_u32_dpp v43, v43, v43 row_ror:2 row_mask:0xf bank_mask:0xf
	s_nop 1
	v_min_u32_dpp v43, v43, v43 row_ror:4 row_mask:0xf bank_mask:0xf
	s_nop 1
	v_min_u32_dpp v43, v43, v43 row_ror:8 row_mask:0xf bank_mask:0xf
	v_add_u32_e32 v43, 1, v43
	v_cmp_eq_u32_e32 vcc, 0, v33
	s_nop 1
	v_cndmask_b32_e32 v34, v34, v43, vcc

.Lp2apr1_iter:
	v_sub_u32_e32 v38, v35, v34
	v_or_b32_e32 v41, 1, v38
	v_ffbh_u32_e32 v41, v41
	v_sub_u32_e32 v41, 26, v41
	v_max_i32_e32 v39, 0, v41
	v_mov_b32_e32 v36, 0
	v_or_b32_e32 v42, 32, v36
	v_lshlrev_b32_e32 v41, v39, v42
	v_add_u32_e64 v43, v34, v41 clamp
	v_mov_b32_e32 v44, 0
	v_cmp_ge_u32_e32 vcc, v0, v43
	v_cmp_ge_u32_e64 s[0:1], v1, v43
	v_cmp_ge_u32_e64 s[2:3], v2, v43
	v_addc_co_u32_e64 v44, vcc, 0, v44, vcc
	v_cmp_ge_u32_e32 vcc, v3, v43
	v_addc_co_u32_e64 v44, s[0:1], 0, v44, s[0:1]
	v_cmp_ge_u32_e64 s[0:1], v4, v43
	v_addc_co_u32_e64 v44, s[2:3], 0, v44, s[2:3]
	v_cmp_ge_u32_e64 s[2:3], v5, v43
	v_addc_co_u32_e64 v44, vcc, 0, v44, vcc
	v_cmp_ge_u32_e32 vcc, v6, v43
	v_addc_co_u32_e64 v44, s[0:1], 0, v44, s[0:1]
	v_cmp_ge_u32_e64 s[0:1], v7, v43
	v_addc_co_u32_e64 v44, s[2:3], 0, v44, s[2:3]
	v_cmp_ge_u32_e64 s[2:3], v8, v43
	v_addc_co_u32_e64 v44, vcc, 0, v44, vcc
	v_cmp_ge_u32_e32 vcc, v9, v43
	v_addc_co_u32_e64 v44, s[0:1], 0, v44, s[0:1]
	v_cmp_ge_u32_e64 s[0:1], v10, v43
	v_addc_co_u32_e64 v44, s[2:3], 0, v44, s[2:3]
	v_cmp_ge_u32_e64 s[2:3], v11, v43
	v_addc_co_u32_e64 v44, vcc, 0, v44, vcc
	v_cmp_ge_u32_e32 vcc, v12, v43
	v_addc_co_u32_e64 v44, s[0:1], 0, v44, s[0:1]
	v_cmp_ge_u32_e64 s[0:1], v13, v43
	v_addc_co_u32_e64 v44, s[2:3], 0, v44, s[2:3]
	v_cmp_ge_u32_e64 s[2:3], v14, v43
	v_addc_co_u32_e64 v44, vcc, 0, v44, vcc
	v_cmp_ge_u32_e32 vcc, v15, v43
	v_addc_co_u32_e64 v44, s[0:1], 0, v44, s[0:1]
	v_cmp_ge_u32_e64 s[0:1], v16, v43
	v_addc_co_u32_e64 v44, s[2:3], 0, v44, s[2:3]
	v_cmp_ge_u32_e64 s[2:3], v17, v43
	v_addc_co_u32_e64 v44, vcc, 0, v44, vcc
	v_cmp_ge_u32_e32 vcc, v18, v43
	v_addc_co_u32_e64 v44, s[0:1], 0, v44, s[0:1]
	v_cmp_ge_u32_e64 s[0:1], v19, v43
	v_addc_co_u32_e64 v44, s[2:3], 0, v44, s[2:3]
	v_cmp_ge_u32_e64 s[2:3], v20, v43
	v_addc_co_u32_e64 v44, vcc, 0, v44, vcc
	v_cmp_ge_u32_e32 vcc, v21, v43
	v_addc_co_u32_e64 v44, s[0:1], 0, v44, s[0:1]
	v_cmp_ge_u32_e64 s[0:1], v22, v43
	v_addc_co_u32_e64 v44, s[2:3], 0, v44, s[2:3]
	v_cmp_ge_u32_e64 s[2:3], v23, v43
	v_addc_co_u32_e64 v44, vcc, 0, v44, vcc
	v_cmp_ge_u32_e32 vcc, v24, v43
	v_addc_co_u32_e64 v44, s[0:1], 0, v44, s[0:1]
	v_cmp_ge_u32_e64 s[0:1], v25, v43
	v_addc_co_u32_e64 v44, s[2:3], 0, v44, s[2:3]
	v_cmp_ge_u32_e64 s[2:3], v26, v43
	v_addc_co_u32_e64 v44, vcc, 0, v44, vcc
	v_cmp_ge_u32_e32 vcc, v27, v43
	v_addc_co_u32_e64 v44, s[0:1], 0, v44, s[0:1]
	v_cmp_ge_u32_e64 s[0:1], v28, v43
	v_addc_co_u32_e64 v44, s[2:3], 0, v44, s[2:3]
	v_cmp_ge_u32_e64 s[2:3], v29, v43
	v_addc_co_u32_e64 v44, vcc, 0, v44, vcc
	v_cmp_ge_u32_e32 vcc, v30, v43
	v_addc_co_u32_e64 v44, s[0:1], 0, v44, s[0:1]
	v_cmp_ge_u32_e64 s[0:1], v31, v43
	v_addc_co_u32_e64 v44, s[2:3], 0, v44, s[2:3]
	v_addc_co_u32_e64 v44, vcc, 0, v44, vcc
	v_addc_co_u32_e64 v44, s[0:1], 0, v44, s[0:1]
	v_mov_b32_e32 v45, v44
	s_nop 1
	v_add_u32_dpp v45, v45, v45 row_ror:1 row_mask:0xf bank_mask:0xf
	s_nop 1
	v_add_u32_dpp v45, v45, v45 row_ror:2 row_mask:0xf bank_mask:0xf
	s_nop 1
	v_add_u32_dpp v45, v45, v45 row_ror:4 row_mask:0xf bank_mask:0xf
	s_nop 1
	v_add_u32_dpp v45, v45, v45 row_ror:8 row_mask:0xf bank_mask:0xf
	s_nop 0
	v_cmp_le_u32_e32 vcc, 0x100, v45
	s_nop 1
	v_cndmask_b32_e32 v36, v36, v42, vcc
	v_cndmask_b32_e32 v46, v46, v45, vcc
	v_cndmask_b32_e32 v47, v47, v44, vcc
	v_or_b32_e32 v42, 16, v36
	v_lshlrev_b32_e32 v41, v39, v42
	v_add_u32_e64 v43, v34, v41 clamp
	v_mov_b32_e32 v44, 0
	v_cmp_ge_u32_e32 vcc, v0, v43
	v_cmp_ge_u32_e64 s[0:1], v1, v43
	v_cmp_ge_u32_e64 s[2:3], v2, v43
	v_addc_co_u32_e64 v44, vcc, 0, v44, vcc
	v_cmp_ge_u32_e32 vcc, v3, v43
	v_addc_co_u32_e64 v44, s[0:1], 0, v44, s[0:1]
	v_cmp_ge_u32_e64 s[0:1], v4, v43
	v_addc_co_u32_e64 v44, s[2:3], 0, v44, s[2:3]
	v_cmp_ge_u32_e64 s[2:3], v5, v43
	v_addc_co_u32_e64 v44, vcc, 0, v44, vcc
	v_cmp_ge_u32_e32 vcc, v6, v43
	v_addc_co_u32_e64 v44, s[0:1], 0, v44, s[0:1]
	v_cmp_ge_u32_e64 s[0:1], v7, v43
	v_addc_co_u32_e64 v44, s[2:3], 0, v44, s[2:3]
	v_cmp_ge_u32_e64 s[2:3], v8, v43
	v_addc_co_u32_e64 v44, vcc, 0, v44, vcc
	v_cmp_ge_u32_e32 vcc, v9, v43
	v_addc_co_u32_e64 v44, s[0:1], 0, v44, s[0:1]
	v_cmp_ge_u32_e64 s[0:1], v10, v43
	v_addc_co_u32_e64 v44, s[2:3], 0, v44, s[2:3]
	v_cmp_ge_u32_e64 s[2:3], v11, v43
	v_addc_co_u32_e64 v44, vcc, 0, v44, vcc
	v_cmp_ge_u32_e32 vcc, v12, v43
	v_addc_co_u32_e64 v44, s[0:1], 0, v44, s[0:1]
	v_cmp_ge_u32_e64 s[0:1], v13, v43
	v_addc_co_u32_e64 v44, s[2:3], 0, v44, s[2:3]
	v_cmp_ge_u32_e64 s[2:3], v14, v43
	v_addc_co_u32_e64 v44, vcc, 0, v44, vcc
	v_cmp_ge_u32_e32 vcc, v15, v43
	v_addc_co_u32_e64 v44, s[0:1], 0, v44, s[0:1]
	v_cmp_ge_u32_e64 s[0:1], v16, v43
	v_addc_co_u32_e64 v44, s[2:3], 0, v44, s[2:3]
	v_cmp_ge_u32_e64 s[2:3], v17, v43
	v_addc_co_u32_e64 v44, vcc, 0, v44, vcc
	v_cmp_ge_u32_e32 vcc, v18, v43
	v_addc_co_u32_e64 v44, s[0:1], 0, v44, s[0:1]
	v_cmp_ge_u32_e64 s[0:1], v19, v43
	v_addc_co_u32_e64 v44, s[2:3], 0, v44, s[2:3]
	v_cmp_ge_u32_e64 s[2:3], v20, v43
	v_addc_co_u32_e64 v44, vcc, 0, v44, vcc
	v_cmp_ge_u32_e32 vcc, v21, v43
	v_addc_co_u32_e64 v44, s[0:1], 0, v44, s[0:1]
	v_cmp_ge_u32_e64 s[0:1], v22, v43
	v_addc_co_u32_e64 v44, s[2:3], 0, v44, s[2:3]
	v_cmp_ge_u32_e64 s[2:3], v23, v43
	v_addc_co_u32_e64 v44, vcc, 0, v44, vcc
	v_cmp_ge_u32_e32 vcc, v24, v43
	v_addc_co_u32_e64 v44, s[0:1], 0, v44, s[0:1]
	v_cmp_ge_u32_e64 s[0:1], v25, v43
	v_addc_co_u32_e64 v44, s[2:3], 0, v44, s[2:3]
	v_cmp_ge_u32_e64 s[2:3], v26, v43
	v_addc_co_u32_e64 v44, vcc, 0, v44, vcc
	v_cmp_ge_u32_e32 vcc, v27, v43
	v_addc_co_u32_e64 v44, s[0:1], 0, v44, s[0:1]
	v_cmp_ge_u32_e64 s[0:1], v28, v43
	v_addc_co_u32_e64 v44, s[2:3], 0, v44, s[2:3]
	v_cmp_ge_u32_e64 s[2:3], v29, v43
	v_addc_co_u32_e64 v44, vcc, 0, v44, vcc
	v_cmp_ge_u32_e32 vcc, v30, v43
	v_addc_co_u32_e64 v44, s[0:1], 0, v44, s[0:1]
	v_cmp_ge_u32_e64 s[0:1], v31, v43
	v_addc_co_u32_e64 v44, s[2:3], 0, v44, s[2:3]
	v_addc_co_u32_e64 v44, vcc, 0, v44, vcc
	v_addc_co_u32_e64 v44, s[0:1], 0, v44, s[0:1]
	v_mov_b32_e32 v45, v44
	s_nop 1
	v_add_u32_dpp v45, v45, v45 row_ror:1 row_mask:0xf bank_mask:0xf
	s_nop 1
	v_add_u32_dpp v45, v45, v45 row_ror:2 row_mask:0xf bank_mask:0xf
	s_nop 1
	v_add_u32_dpp v45, v45, v45 row_ror:4 row_mask:0xf bank_mask:0xf
	s_nop 1
	v_add_u32_dpp v45, v45, v45 row_ror:8 row_mask:0xf bank_mask:0xf
	s_nop 0
	v_cmp_le_u32_e32 vcc, 0x100, v45
	s_nop 1
	v_cndmask_b32_e32 v36, v36, v42, vcc
	v_cndmask_b32_e32 v46, v46, v45, vcc
	v_cndmask_b32_e32 v47, v47, v44, vcc
	v_or_b32_e32 v42, 8, v36
	v_lshlrev_b32_e32 v41, v39, v42
	v_add_u32_e64 v43, v34, v41 clamp
	v_mov_b32_e32 v44, 0
	v_cmp_ge_u32_e32 vcc, v0, v43
	v_cmp_ge_u32_e64 s[0:1], v1, v43
	v_cmp_ge_u32_e64 s[2:3], v2, v43
	v_addc_co_u32_e64 v44, vcc, 0, v44, vcc
	v_cmp_ge_u32_e32 vcc, v3, v43
	v_addc_co_u32_e64 v44, s[0:1], 0, v44, s[0:1]
	v_cmp_ge_u32_e64 s[0:1], v4, v43
	v_addc_co_u32_e64 v44, s[2:3], 0, v44, s[2:3]
	v_cmp_ge_u32_e64 s[2:3], v5, v43
	v_addc_co_u32_e64 v44, vcc, 0, v44, vcc
	v_cmp_ge_u32_e32 vcc, v6, v43
	v_addc_co_u32_e64 v44, s[0:1], 0, v44, s[0:1]
	v_cmp_ge_u32_e64 s[0:1], v7, v43
	v_addc_co_u32_e64 v44, s[2:3], 0, v44, s[2:3]
	v_cmp_ge_u32_e64 s[2:3], v8, v43
	v_addc_co_u32_e64 v44, vcc, 0, v44, vcc
	v_cmp_ge_u32_e32 vcc, v9, v43
	v_addc_co_u32_e64 v44, s[0:1], 0, v44, s[0:1]
	v_cmp_ge_u32_e64 s[0:1], v10, v43
	v_addc_co_u32_e64 v44, s[2:3], 0, v44, s[2:3]
	v_cmp_ge_u32_e64 s[2:3], v11, v43
	v_addc_co_u32_e64 v44, vcc, 0, v44, vcc
	v_cmp_ge_u32_e32 vcc, v12, v43
	v_addc_co_u32_e64 v44, s[0:1], 0, v44, s[0:1]
	v_cmp_ge_u32_e64 s[0:1], v13, v43
	v_addc_co_u32_e64 v44, s[2:3], 0, v44, s[2:3]
	v_cmp_ge_u32_e64 s[2:3], v14, v43
	v_addc_co_u32_e64 v44, vcc, 0, v44, vcc
	v_cmp_ge_u32_e32 vcc, v15, v43
	v_addc_co_u32_e64 v44, s[0:1], 0, v44, s[0:1]
	v_cmp_ge_u32_e64 s[0:1], v16, v43
	v_addc_co_u32_e64 v44, s[2:3], 0, v44, s[2:3]
	v_cmp_ge_u32_e64 s[2:3], v17, v43
	v_addc_co_u32_e64 v44, vcc, 0, v44, vcc
	v_cmp_ge_u32_e32 vcc, v18, v43
	v_addc_co_u32_e64 v44, s[0:1], 0, v44, s[0:1]
	v_cmp_ge_u32_e64 s[0:1], v19, v43
	v_addc_co_u32_e64 v44, s[2:3], 0, v44, s[2:3]
	v_cmp_ge_u32_e64 s[2:3], v20, v43
	v_addc_co_u32_e64 v44, vcc, 0, v44, vcc
	v_cmp_ge_u32_e32 vcc, v21, v43
	v_addc_co_u32_e64 v44, s[0:1], 0, v44, s[0:1]
	v_cmp_ge_u32_e64 s[0:1], v22, v43
	v_addc_co_u32_e64 v44, s[2:3], 0, v44, s[2:3]
	v_cmp_ge_u32_e64 s[2:3], v23, v43
	v_addc_co_u32_e64 v44, vcc, 0, v44, vcc
	v_cmp_ge_u32_e32 vcc, v24, v43
	v_addc_co_u32_e64 v44, s[0:1], 0, v44, s[0:1]
	v_cmp_ge_u32_e64 s[0:1], v25, v43
	v_addc_co_u32_e64 v44, s[2:3], 0, v44, s[2:3]
	v_cmp_ge_u32_e64 s[2:3], v26, v43
	v_addc_co_u32_e64 v44, vcc, 0, v44, vcc
	v_cmp_ge_u32_e32 vcc, v27, v43
	v_addc_co_u32_e64 v44, s[0:1], 0, v44, s[0:1]
	v_cmp_ge_u32_e64 s[0:1], v28, v43
	v_addc_co_u32_e64 v44, s[2:3], 0, v44, s[2:3]
	v_cmp_ge_u32_e64 s[2:3], v29, v43
	v_addc_co_u32_e64 v44, vcc, 0, v44, vcc
	v_cmp_ge_u32_e32 vcc, v30, v43
	v_addc_co_u32_e64 v44, s[0:1], 0, v44, s[0:1]
	v_cmp_ge_u32_e64 s[0:1], v31, v43
	v_addc_co_u32_e64 v44, s[2:3], 0, v44, s[2:3]
	v_addc_co_u32_e64 v44, vcc, 0, v44, vcc
	v_addc_co_u32_e64 v44, s[0:1], 0, v44, s[0:1]
	v_mov_b32_e32 v45, v44
	s_nop 1
	v_add_u32_dpp v45, v45, v45 row_ror:1 row_mask:0xf bank_mask:0xf
	s_nop 1
	v_add_u32_dpp v45, v45, v45 row_ror:2 row_mask:0xf bank_mask:0xf
	s_nop 1
	v_add_u32_dpp v45, v45, v45 row_ror:4 row_mask:0xf bank_mask:0xf
	s_nop 1
	v_add_u32_dpp v45, v45, v45 row_ror:8 row_mask:0xf bank_mask:0xf
	s_nop 0
	v_cmp_le_u32_e32 vcc, 0x100, v45
	s_nop 1
	v_cndmask_b32_e32 v36, v36, v42, vcc
	v_cndmask_b32_e32 v46, v46, v45, vcc
	v_cndmask_b32_e32 v47, v47, v44, vcc
	v_or_b32_e32 v42, 4, v36
	v_lshlrev_b32_e32 v41, v39, v42
	v_add_u32_e64 v43, v34, v41 clamp
	v_mov_b32_e32 v44, 0
	v_cmp_ge_u32_e32 vcc, v0, v43
	v_cmp_ge_u32_e64 s[0:1], v1, v43
	v_cmp_ge_u32_e64 s[2:3], v2, v43
	v_addc_co_u32_e64 v44, vcc, 0, v44, vcc
	v_cmp_ge_u32_e32 vcc, v3, v43
	v_addc_co_u32_e64 v44, s[0:1], 0, v44, s[0:1]
	v_cmp_ge_u32_e64 s[0:1], v4, v43
	v_addc_co_u32_e64 v44, s[2:3], 0, v44, s[2:3]
	v_cmp_ge_u32_e64 s[2:3], v5, v43
	v_addc_co_u32_e64 v44, vcc, 0, v44, vcc
	v_cmp_ge_u32_e32 vcc, v6, v43
	v_addc_co_u32_e64 v44, s[0:1], 0, v44, s[0:1]
	v_cmp_ge_u32_e64 s[0:1], v7, v43
	v_addc_co_u32_e64 v44, s[2:3], 0, v44, s[2:3]
	v_cmp_ge_u32_e64 s[2:3], v8, v43
	v_addc_co_u32_e64 v44, vcc, 0, v44, vcc
	v_cmp_ge_u32_e32 vcc, v9, v43
	v_addc_co_u32_e64 v44, s[0:1], 0, v44, s[0:1]
	v_cmp_ge_u32_e64 s[0:1], v10, v43
	v_addc_co_u32_e64 v44, s[2:3], 0, v44, s[2:3]
	v_cmp_ge_u32_e64 s[2:3], v11, v43
	v_addc_co_u32_e64 v44, vcc, 0, v44, vcc
	v_cmp_ge_u32_e32 vcc, v12, v43
	v_addc_co_u32_e64 v44, s[0:1], 0, v44, s[0:1]
	v_cmp_ge_u32_e64 s[0:1], v13, v43
	v_addc_co_u32_e64 v44, s[2:3], 0, v44, s[2:3]
	v_cmp_ge_u32_e64 s[2:3], v14, v43
	v_addc_co_u32_e64 v44, vcc, 0, v44, vcc
	v_cmp_ge_u32_e32 vcc, v15, v43
	v_addc_co_u32_e64 v44, s[0:1], 0, v44, s[0:1]
	v_cmp_ge_u32_e64 s[0:1], v16, v43
	v_addc_co_u32_e64 v44, s[2:3], 0, v44, s[2:3]
	v_cmp_ge_u32_e64 s[2:3], v17, v43
	v_addc_co_u32_e64 v44, vcc, 0, v44, vcc
	v_cmp_ge_u32_e32 vcc, v18, v43
	v_addc_co_u32_e64 v44, s[0:1], 0, v44, s[0:1]
	v_cmp_ge_u32_e64 s[0:1], v19, v43
	v_addc_co_u32_e64 v44, s[2:3], 0, v44, s[2:3]
	v_cmp_ge_u32_e64 s[2:3], v20, v43
	v_addc_co_u32_e64 v44, vcc, 0, v44, vcc
	v_cmp_ge_u32_e32 vcc, v21, v43
	v_addc_co_u32_e64 v44, s[0:1], 0, v44, s[0:1]
	v_cmp_ge_u32_e64 s[0:1], v22, v43
	v_addc_co_u32_e64 v44, s[2:3], 0, v44, s[2:3]
	v_cmp_ge_u32_e64 s[2:3], v23, v43
	v_addc_co_u32_e64 v44, vcc, 0, v44, vcc
	v_cmp_ge_u32_e32 vcc, v24, v43
	v_addc_co_u32_e64 v44, s[0:1], 0, v44, s[0:1]
	v_cmp_ge_u32_e64 s[0:1], v25, v43
	v_addc_co_u32_e64 v44, s[2:3], 0, v44, s[2:3]
	v_cmp_ge_u32_e64 s[2:3], v26, v43
	v_addc_co_u32_e64 v44, vcc, 0, v44, vcc
	v_cmp_ge_u32_e32 vcc, v27, v43
	v_addc_co_u32_e64 v44, s[0:1], 0, v44, s[0:1]
	v_cmp_ge_u32_e64 s[0:1], v28, v43
	v_addc_co_u32_e64 v44, s[2:3], 0, v44, s[2:3]
	v_cmp_ge_u32_e64 s[2:3], v29, v43
	v_addc_co_u32_e64 v44, vcc, 0, v44, vcc
	v_cmp_ge_u32_e32 vcc, v30, v43
	v_addc_co_u32_e64 v44, s[0:1], 0, v44, s[0:1]
	v_cmp_ge_u32_e64 s[0:1], v31, v43
	v_addc_co_u32_e64 v44, s[2:3], 0, v44, s[2:3]
	v_addc_co_u32_e64 v44, vcc, 0, v44, vcc
	v_addc_co_u32_e64 v44, s[0:1], 0, v44, s[0:1]
	v_mov_b32_e32 v45, v44
	s_nop 1
	v_add_u32_dpp v45, v45, v45 row_ror:1 row_mask:0xf bank_mask:0xf
	s_nop 1
	v_add_u32_dpp v45, v45, v45 row_ror:2 row_mask:0xf bank_mask:0xf
	s_nop 1
	v_add_u32_dpp v45, v45, v45 row_ror:4 row_mask:0xf bank_mask:0xf
	s_nop 1
	v_add_u32_dpp v45, v45, v45 row_ror:8 row_mask:0xf bank_mask:0xf
	s_nop 0
	v_cmp_le_u32_e32 vcc, 0x100, v45
	s_nop 1
	v_cndmask_b32_e32 v36, v36, v42, vcc
	v_cndmask_b32_e32 v46, v46, v45, vcc
	v_cndmask_b32_e32 v47, v47, v44, vcc
	v_or_b32_e32 v42, 2, v36
	v_lshlrev_b32_e32 v41, v39, v42
	v_add_u32_e64 v43, v34, v41 clamp
	v_mov_b32_e32 v44, 0
	v_cmp_ge_u32_e32 vcc, v0, v43
	v_cmp_ge_u32_e64 s[0:1], v1, v43
	v_cmp_ge_u32_e64 s[2:3], v2, v43
	v_addc_co_u32_e64 v44, vcc, 0, v44, vcc
	v_cmp_ge_u32_e32 vcc, v3, v43
	v_addc_co_u32_e64 v44, s[0:1], 0, v44, s[0:1]
	v_cmp_ge_u32_e64 s[0:1], v4, v43
	v_addc_co_u32_e64 v44, s[2:3], 0, v44, s[2:3]
	v_cmp_ge_u32_e64 s[2:3], v5, v43
	v_addc_co_u32_e64 v44, vcc, 0, v44, vcc
	v_cmp_ge_u32_e32 vcc, v6, v43
	v_addc_co_u32_e64 v44, s[0:1], 0, v44, s[0:1]
	v_cmp_ge_u32_e64 s[0:1], v7, v43
	v_addc_co_u32_e64 v44, s[2:3], 0, v44, s[2:3]
	v_cmp_ge_u32_e64 s[2:3], v8, v43
	v_addc_co_u32_e64 v44, vcc, 0, v44, vcc
	v_cmp_ge_u32_e32 vcc, v9, v43
	v_addc_co_u32_e64 v44, s[0:1], 0, v44, s[0:1]
	v_cmp_ge_u32_e64 s[0:1], v10, v43
	v_addc_co_u32_e64 v44, s[2:3], 0, v44, s[2:3]
	v_cmp_ge_u32_e64 s[2:3], v11, v43
	v_addc_co_u32_e64 v44, vcc, 0, v44, vcc
	v_cmp_ge_u32_e32 vcc, v12, v43
	v_addc_co_u32_e64 v44, s[0:1], 0, v44, s[0:1]
	v_cmp_ge_u32_e64 s[0:1], v13, v43
	v_addc_co_u32_e64 v44, s[2:3], 0, v44, s[2:3]
	v_cmp_ge_u32_e64 s[2:3], v14, v43
	v_addc_co_u32_e64 v44, vcc, 0, v44, vcc
	v_cmp_ge_u32_e32 vcc, v15, v43
	v_addc_co_u32_e64 v44, s[0:1], 0, v44, s[0:1]
	v_cmp_ge_u32_e64 s[0:1], v16, v43
	v_addc_co_u32_e64 v44, s[2:3], 0, v44, s[2:3]
	v_cmp_ge_u32_e64 s[2:3], v17, v43
	v_addc_co_u32_e64 v44, vcc, 0, v44, vcc
	v_cmp_ge_u32_e32 vcc, v18, v43
	v_addc_co_u32_e64 v44, s[0:1], 0, v44, s[0:1]
	v_cmp_ge_u32_e64 s[0:1], v19, v43
	v_addc_co_u32_e64 v44, s[2:3], 0, v44, s[2:3]
	v_cmp_ge_u32_e64 s[2:3], v20, v43
	v_addc_co_u32_e64 v44, vcc, 0, v44, vcc
	v_cmp_ge_u32_e32 vcc, v21, v43
	v_addc_co_u32_e64 v44, s[0:1], 0, v44, s[0:1]
	v_cmp_ge_u32_e64 s[0:1], v22, v43
	v_addc_co_u32_e64 v44, s[2:3], 0, v44, s[2:3]
	v_cmp_ge_u32_e64 s[2:3], v23, v43
	v_addc_co_u32_e64 v44, vcc, 0, v44, vcc
	v_cmp_ge_u32_e32 vcc, v24, v43
	v_addc_co_u32_e64 v44, s[0:1], 0, v44, s[0:1]
	v_cmp_ge_u32_e64 s[0:1], v25, v43
	v_addc_co_u32_e64 v44, s[2:3], 0, v44, s[2:3]
	v_cmp_ge_u32_e64 s[2:3], v26, v43
	v_addc_co_u32_e64 v44, vcc, 0, v44, vcc
	v_cmp_ge_u32_e32 vcc, v27, v43
	v_addc_co_u32_e64 v44, s[0:1], 0, v44, s[0:1]
	v_cmp_ge_u32_e64 s[0:1], v28, v43
	v_addc_co_u32_e64 v44, s[2:3], 0, v44, s[2:3]
	v_cmp_ge_u32_e64 s[2:3], v29, v43
	v_addc_co_u32_e64 v44, vcc, 0, v44, vcc
	v_cmp_ge_u32_e32 vcc, v30, v43
	v_addc_co_u32_e64 v44, s[0:1], 0, v44, s[0:1]
	v_cmp_ge_u32_e64 s[0:1], v31, v43
	v_addc_co_u32_e64 v44, s[2:3], 0, v44, s[2:3]
	v_addc_co_u32_e64 v44, vcc, 0, v44, vcc
	v_addc_co_u32_e64 v44, s[0:1], 0, v44, s[0:1]
	v_mov_b32_e32 v45, v44
	s_nop 1
	v_add_u32_dpp v45, v45, v45 row_ror:1 row_mask:0xf bank_mask:0xf
	s_nop 1
	v_add_u32_dpp v45, v45, v45 row_ror:2 row_mask:0xf bank_mask:0xf
	s_nop 1
	v_add_u32_dpp v45, v45, v45 row_ror:4 row_mask:0xf bank_mask:0xf
	s_nop 1
	v_add_u32_dpp v45, v45, v45 row_ror:8 row_mask:0xf bank_mask:0xf
	s_nop 0
	v_cmp_le_u32_e32 vcc, 0x100, v45
	s_nop 1
	v_cndmask_b32_e32 v36, v36, v42, vcc
	v_cndmask_b32_e32 v46, v46, v45, vcc
	v_cndmask_b32_e32 v47, v47, v44, vcc
	v_or_b32_e32 v42, 1, v36
	v_lshlrev_b32_e32 v41, v39, v42
	v_add_u32_e64 v43, v34, v41 clamp
	v_mov_b32_e32 v44, 0
	v_cmp_ge_u32_e32 vcc, v0, v43
	v_cmp_ge_u32_e64 s[0:1], v1, v43
	v_cmp_ge_u32_e64 s[2:3], v2, v43
	v_addc_co_u32_e64 v44, vcc, 0, v44, vcc
	v_cmp_ge_u32_e32 vcc, v3, v43
	v_addc_co_u32_e64 v44, s[0:1], 0, v44, s[0:1]
	v_cmp_ge_u32_e64 s[0:1], v4, v43
	v_addc_co_u32_e64 v44, s[2:3], 0, v44, s[2:3]
	v_cmp_ge_u32_e64 s[2:3], v5, v43
	v_addc_co_u32_e64 v44, vcc, 0, v44, vcc
	v_cmp_ge_u32_e32 vcc, v6, v43
	v_addc_co_u32_e64 v44, s[0:1], 0, v44, s[0:1]
	v_cmp_ge_u32_e64 s[0:1], v7, v43
	v_addc_co_u32_e64 v44, s[2:3], 0, v44, s[2:3]
	v_cmp_ge_u32_e64 s[2:3], v8, v43
	v_addc_co_u32_e64 v44, vcc, 0, v44, vcc
	v_cmp_ge_u32_e32 vcc, v9, v43
	v_addc_co_u32_e64 v44, s[0:1], 0, v44, s[0:1]
	v_cmp_ge_u32_e64 s[0:1], v10, v43
	v_addc_co_u32_e64 v44, s[2:3], 0, v44, s[2:3]
	v_cmp_ge_u32_e64 s[2:3], v11, v43
	v_addc_co_u32_e64 v44, vcc, 0, v44, vcc
	v_cmp_ge_u32_e32 vcc, v12, v43
	v_addc_co_u32_e64 v44, s[0:1], 0, v44, s[0:1]
	v_cmp_ge_u32_e64 s[0:1], v13, v43
	v_addc_co_u32_e64 v44, s[2:3], 0, v44, s[2:3]
	v_cmp_ge_u32_e64 s[2:3], v14, v43
	v_addc_co_u32_e64 v44, vcc, 0, v44, vcc
	v_cmp_ge_u32_e32 vcc, v15, v43
	v_addc_co_u32_e64 v44, s[0:1], 0, v44, s[0:1]
	v_cmp_ge_u32_e64 s[0:1], v16, v43
	v_addc_co_u32_e64 v44, s[2:3], 0, v44, s[2:3]
	v_cmp_ge_u32_e64 s[2:3], v17, v43
	v_addc_co_u32_e64 v44, vcc, 0, v44, vcc
	v_cmp_ge_u32_e32 vcc, v18, v43
	v_addc_co_u32_e64 v44, s[0:1], 0, v44, s[0:1]
	v_cmp_ge_u32_e64 s[0:1], v19, v43
	v_addc_co_u32_e64 v44, s[2:3], 0, v44, s[2:3]
	v_cmp_ge_u32_e64 s[2:3], v20, v43
	v_addc_co_u32_e64 v44, vcc, 0, v44, vcc
	v_cmp_ge_u32_e32 vcc, v21, v43
	v_addc_co_u32_e64 v44, s[0:1], 0, v44, s[0:1]
	v_cmp_ge_u32_e64 s[0:1], v22, v43
	v_addc_co_u32_e64 v44, s[2:3], 0, v44, s[2:3]
	v_cmp_ge_u32_e64 s[2:3], v23, v43
	v_addc_co_u32_e64 v44, vcc, 0, v44, vcc
	v_cmp_ge_u32_e32 vcc, v24, v43
	v_addc_co_u32_e64 v44, s[0:1], 0, v44, s[0:1]
	v_cmp_ge_u32_e64 s[0:1], v25, v43
	v_addc_co_u32_e64 v44, s[2:3], 0, v44, s[2:3]
	v_cmp_ge_u32_e64 s[2:3], v26, v43
	v_addc_co_u32_e64 v44, vcc, 0, v44, vcc
	v_cmp_ge_u32_e32 vcc, v27, v43
	v_addc_co_u32_e64 v44, s[0:1], 0, v44, s[0:1]
	v_cmp_ge_u32_e64 s[0:1], v28, v43
	v_addc_co_u32_e64 v44, s[2:3], 0, v44, s[2:3]
	v_cmp_ge_u32_e64 s[2:3], v29, v43
	v_addc_co_u32_e64 v44, vcc, 0, v44, vcc
	v_cmp_ge_u32_e32 vcc, v30, v43
	v_addc_co_u32_e64 v44, s[0:1], 0, v44, s[0:1]
	v_cmp_ge_u32_e64 s[0:1], v31, v43
	v_addc_co_u32_e64 v44, s[2:3], 0, v44, s[2:3]
	v_addc_co_u32_e64 v44, vcc, 0, v44, vcc
	v_addc_co_u32_e64 v44, s[0:1], 0, v44, s[0:1]
	v_mov_b32_e32 v45, v44
	s_nop 1
	v_add_u32_dpp v45, v45, v45 row_ror:1 row_mask:0xf bank_mask:0xf
	s_nop 1
	v_add_u32_dpp v45, v45, v45 row_ror:2 row_mask:0xf bank_mask:0xf
	s_nop 1
	v_add_u32_dpp v45, v45, v45 row_ror:4 row_mask:0xf bank_mask:0xf
	s_nop 1
	v_add_u32_dpp v45, v45, v45 row_ror:8 row_mask:0xf bank_mask:0xf
	s_nop 0
	v_cmp_le_u32_e32 vcc, 0x100, v45
	s_nop 1
	v_cndmask_b32_e32 v36, v36, v42, vcc
	v_cndmask_b32_e32 v46, v46, v45, vcc
	v_cndmask_b32_e32 v47, v47, v44, vcc
	v_lshlrev_b32_e32 v41, v39, v36
	v_add_u32_e32 v41, v34, v41
	v_cmp_ge_u32_e32 vcc, 0x120, v46
	v_cmp_eq_u32_e64 s[0:1], 0, v39
	v_lshlrev_b32_e32 v42, v39, v200
	v_add_u32_e32 v42, -1, v42
	s_or_b64 vcc, vcc, s[0:1]
	s_andn2_b64 s[0:1], vcc, s[50:51]
	s_nor_b64 s[2:3], vcc, s[50:51]
	s_or_b64 s[50:51], s[50:51], vcc
	v_add_u32_e64 v42, v41, v42 clamp
	v_min_u32_e32 v42, v42, v35
	v_cndmask_b32_e64 v37, v37, v41, s[0:1]
	v_cndmask_b32_e64 v62, v62, v47, s[0:1]
	v_cndmask_b32_e64 v35, v35, v42, s[2:3]
	v_cndmask_b32_e64 v34, v34, v41, s[2:3]
	s_cmp_eq_u64 s[50:51], -1
	s_cbranch_scc0 .Lp2apr1_iter
	s_mov_b64 exec, s[22:23]
	v_mov_b32_e32 v61, v62
	s_nop 1
	v_add_u32_dpp v61, v61, v61 row_shr:1 row_mask:0xf bank_mask:0xf bound_ctrl:1
	s_nop 1
	v_add_u32_dpp v61, v61, v61 row_shr:2 row_mask:0xf bank_mask:0xf bound_ctrl:1
	s_nop 1
	v_add_u32_dpp v61, v61, v61 row_shr:4 row_mask:0xf bank_mask:0xf bound_ctrl:1
	s_nop 1
	v_add_u32_dpp v61, v61, v61 row_shr:8 row_mask:0xf bank_mask:0xf bound_ctrl:1
	v_sub_u32_e32 v62, v61, v62
	v_lshl_add_u32 v41, v62, 2, v59
	v_cmpx_ge_u32_e32 vcc, v0, v37
	ds_write_b32 v41, v0
	v_add_u32_e32 v62, 1, v62
	s_mov_b64 exec, s[22:23]
	v_lshl_add_u32 v41, v62, 2, v59
	v_cmpx_ge_u32_e32 vcc, v1, v37
	ds_write_b32 v41, v1
	v_add_u32_e32 v62, 1, v62
	s_mov_b64 exec, s[22:23]
	v_lshl_add_u32 v41, v62, 2, v59
	v_cmpx_ge_u32_e32 vcc, v2, v37
	ds_write_b32 v41, v2
	v_add_u32_e32 v62, 1, v62
	s_mov_b64 exec, s[22:23]
	v_lshl_add_u32 v41, v62, 2, v59
	v_cmpx_ge_u32_e32 vcc, v3, v37
	ds_write_b32 v41, v3
	v_add_u32_e32 v62, 1, v62
	s_mov_b64 exec, s[22:23]
	v_lshl_add_u32 v41, v62, 2, v59
	v_cmpx_ge_u32_e32 vcc, v4, v37
	ds_write_b32 v41, v4
	v_add_u32_e32 v62, 1, v62
	s_mov_b64 exec, s[22:23]
	v_lshl_add_u32 v41, v62, 2, v59
	v_cmpx_ge_u32_e32 vcc, v5, v37
	ds_write_b32 v41, v5
	v_add_u32_e32 v62, 1, v62
	s_mov_b64 exec, s[22:23]
	v_lshl_add_u32 v41, v62, 2, v59
	v_cmpx_ge_u32_e32 vcc, v6, v37
	ds_write_b32 v41, v6
	v_add_u32_e32 v62, 1, v62
	s_mov_b64 exec, s[22:23]
	v_lshl_add_u32 v41, v62, 2, v59
	v_cmpx_ge_u32_e32 vcc, v7, v37
	ds_write_b32 v41, v7
	v_add_u32_e32 v62, 1, v62
	s_mov_b64 exec, s[22:23]
	v_lshl_add_u32 v41, v62, 2, v59
	v_cmpx_ge_u32_e32 vcc, v8, v37
	ds_write_b32 v41, v8
	v_add_u32_e32 v62, 1, v62
	s_mov_b64 exec, s[22:23]
	v_lshl_add_u32 v41, v62, 2, v59
	v_cmpx_ge_u32_e32 vcc, v9, v37
	ds_write_b32 v41, v9
	v_add_u32_e32 v62, 1, v62
	s_mov_b64 exec, s[22:23]
	v_lshl_add_u32 v41, v62, 2, v59
	v_cmpx_ge_u32_e32 vcc, v10, v37
	ds_write_b32 v41, v10
	v_add_u32_e32 v62, 1, v62
	s_mov_b64 exec, s[22:23]
	v_lshl_add_u32 v41, v62, 2, v59
	v_cmpx_ge_u32_e32 vcc, v11, v37
	ds_write_b32 v41, v11
	v_add_u32_e32 v62, 1, v62
	s_mov_b64 exec, s[22:23]
	v_lshl_add_u32 v41, v62, 2, v59
	v_cmpx_ge_u32_e32 vcc, v12, v37
	ds_write_b32 v41, v12
	v_add_u32_e32 v62, 1, v62
	s_mov_b64 exec, s[22:23]
	v_lshl_add_u32 v41, v62, 2, v59
	v_cmpx_ge_u32_e32 vcc, v13, v37
	ds_write_b32 v41, v13
	v_add_u32_e32 v62, 1, v62
	s_mov_b64 exec, s[22:23]
	v_lshl_add_u32 v41, v62, 2, v59
	v_cmpx_ge_u32_e32 vcc, v14, v37
	ds_write_b32 v41, v14
	v_add_u32_e32 v62, 1, v62
	s_mov_b64 exec, s[22:23]
	v_lshl_add_u32 v41, v62, 2, v59
	v_cmpx_ge_u32_e32 vcc, v15, v37
	ds_write_b32 v41, v15
	v_add_u32_e32 v62, 1, v62
	s_mov_b64 exec, s[22:23]
	v_lshl_add_u32 v41, v62, 2, v59
	v_cmpx_ge_u32_e32 vcc, v16, v37
	ds_write_b32 v41, v16
	v_add_u32_e32 v62, 1, v62
	s_mov_b64 exec, s[22:23]
	v_lshl_add_u32 v41, v62, 2, v59
	v_cmpx_ge_u32_e32 vcc, v17, v37
	ds_write_b32 v41, v17
	v_add_u32_e32 v62, 1, v62
	s_mov_b64 exec, s[22:23]
	v_lshl_add_u32 v41, v62, 2, v59
	v_cmpx_ge_u32_e32 vcc, v18, v37
	ds_write_b32 v41, v18
	v_add_u32_e32 v62, 1, v62
	s_mov_b64 exec, s[22:23]
	v_lshl_add_u32 v41, v62, 2, v59
	v_cmpx_ge_u32_e32 vcc, v19, v37
	ds_write_b32 v41, v19
	v_add_u32_e32 v62, 1, v62
	s_mov_b64 exec, s[22:23]
	v_lshl_add_u32 v41, v62, 2, v59
	v_cmpx_ge_u32_e32 vcc, v20, v37
	ds_write_b32 v41, v20
	v_add_u32_e32 v62, 1, v62
	s_mov_b64 exec, s[22:23]
	v_lshl_add_u32 v41, v62, 2, v59
	v_cmpx_ge_u32_e32 vcc, v21, v37
	ds_write_b32 v41, v21
	v_add_u32_e32 v62, 1, v62
	s_mov_b64 exec, s[22:23]
	v_lshl_add_u32 v41, v62, 2, v59
	v_cmpx_ge_u32_e32 vcc, v22, v37
	ds_write_b32 v41, v22
	v_add_u32_e32 v62, 1, v62
	s_mov_b64 exec, s[22:23]
	v_lshl_add_u32 v41, v62, 2, v59
	v_cmpx_ge_u32_e32 vcc, v23, v37
	ds_write_b32 v41, v23
	v_add_u32_e32 v62, 1, v62
	s_mov_b64 exec, s[22:23]
	v_lshl_add_u32 v41, v62, 2, v59
	v_cmpx_ge_u32_e32 vcc, v24, v37
	ds_write_b32 v41, v24
	v_add_u32_e32 v62, 1, v62
	s_mov_b64 exec, s[22:23]
	v_lshl_add_u32 v41, v62, 2, v59
	v_cmpx_ge_u32_e32 vcc, v25, v37
	ds_write_b32 v41, v25
	v_add_u32_e32 v62, 1, v62
	s_mov_b64 exec, s[22:23]
	v_lshl_add_u32 v41, v62, 2, v59
	v_cmpx_ge_u32_e32 vcc, v26, v37
	ds_write_b32 v41, v26
	v_add_u32_e32 v62, 1, v62
	s_mov_b64 exec, s[22:23]
	v_lshl_add_u32 v41, v62, 2, v59
	v_cmpx_ge_u32_e32 vcc, v27, v37
	ds_write_b32 v41, v27
	v_add_u32_e32 v62, 1, v62
	s_mov_b64 exec, s[22:23]
	v_lshl_add_u32 v41, v62, 2, v59
	v_cmpx_ge_u32_e32 vcc, v28, v37
	ds_write_b32 v41, v28
	v_add_u32_e32 v62, 1, v62
	s_mov_b64 exec, s[22:23]
	v_lshl_add_u32 v41, v62, 2, v59
	v_cmpx_ge_u32_e32 vcc, v29, v37
	ds_write_b32 v41, v29
	v_add_u32_e32 v62, 1, v62
	s_mov_b64 exec, s[22:23]
	v_lshl_add_u32 v41, v62, 2, v59
	v_cmpx_ge_u32_e32 vcc, v30, v37
	ds_write_b32 v41, v30
	v_add_u32_e32 v62, 1, v62
	s_mov_b64 exec, s[22:23]
	v_lshl_add_u32 v41, v62, 2, v59
	v_cmpx_ge_u32_e32 vcc, v31, v37
	ds_write_b32 v41, v31
	v_add_u32_e32 v62, 1, v62
	s_mov_b64 exec, s[22:23]
	s_mov_b64 exec, -1
	v_and_b32_e32 v41, 0xffffe000, v37
	v_ashrrev_i32_e32 v42, 31, v41
	v_not_b32_e32 v42, v42
	v_or_b32_e32 v42, 0x80000000, v42
	v_xor_b32_e32 v63, v41, v42
	s_cmpk_lt_i32 s8, 0x121
	s_cbranch_scc1 .Lp2apr1_o0
	v_readlane_b32 s0, v63, 0
	v_readlane_b32 s74, v37, 0
	v_readlane_b32 s8, v61, 15
	v_mov_b32_e32 v233, s0
.Lp2apr1_o0:
	s_cmpk_lt_i32 s14, 0x121
	s_cbranch_scc1 .Lp2apr1_o1
	v_readlane_b32 s0, v63, 16
	v_readlane_b32 s75, v37, 16
	v_readlane_b32 s14, v61, 31
	v_mov_b32_e32 v234, s0
.Lp2apr1_o1:
	s_cmpk_lt_i32 s13, 0x121
	s_cbranch_scc1 .Lp2apr1_o2
	v_readlane_b32 s0, v63, 32
	v_readlane_b32 s76, v37, 32
	v_readlane_b32 s13, v61, 47
	v_mov_b32_e32 v235, s0
.Lp2apr1_o2:
	s_cmpk_lt_i32 s5, 0x121
	s_cbranch_scc1 .Lp2apr1_o3
	v_readlane_b32 s0, v63, 48
	v_readlane_b32 s77, v37, 48
	v_readlane_b32 s5, v61, 63
	v_mov_b32_e32 v236, s0
